# phase-6 rstd prologue: 4 loads + permlane16/32 exchange instead of 16 loads in 4 serial round trips (same f32 association)
# speedup vs baseline: 1.0155x; 1.0006x over previous
; DI int BIDX() { int b = blockIdx.x; asm volatile("" : "+s"(b)); return b; }
; DI int tile_groups(int MT, int NT) { return (MT >> 6) * ((NT + 7) >> 3) * 512; }
; DI void load_rstd(float (&rs)[4], const float* ssq, int row0, int lr) {
; #pragma unroll
;   for (int mt = 0; mt < 4; ++mt) {
;     const float4* q = (const float4*)(ssq + (size_t)(row0 + mt * 16 + lr) * 16);
;     const float4 a = q[0], b = q[1], c = q[2], d = q[3];
;     const float s = ((a.x + a.y) + (a.z + a.w)) + ((b.x + b.y) + (b.z + b.w)) + ((c.x + c.y) + (c.z + c.w)) + ((d.x + d.y) + (d.z + d.w));
;     rs[mt] = rsqrtf(s * (1.0f / 1024.0f) + EPS);
;   }
; }
; template <int VAR> DI void phase_up(const Params& P, int l, char* smem) {
;     ...
;   for (int vb = BIDX(); vb < tile_groups(128, 32); vb += gridDim.x) {
;     int tm, tn; if (!tile_of(vb, 128, 32, tm, tn)) continue;
;     const int m0 = tm * 128, n0 = tn * 128;
;     const int row0 = m0 + wm * 64, col0 = n0 + wn * 64;
;     f32x4 acc[4][4]; zero_acc(acc);
;     float rs[4]; load_rstd(rs, ssq, row0, lr);
.LBB0_1313:
	s_ashr_i32 s4, s2, 9
	s_lshr_b32 s1, s4, 30
	s_add_i32 s1, s4, s1
	s_ashr_i32 s5, s1, 2
	s_lshl_b32 s1, s5, 6
	s_and_b32 s6, s12, 56
	s_lshl_b32 s5, s5, 5
	s_lshl_b32 s4, s4, 3
	s_or_b32 s1, s1, s6
	s_bfe_u32 s6, s2, 0x30003
	s_sub_i32 s4, s4, s5
	s_bfe_u32 s5, s2, 0x30006
	s_or_b32 s1, s1, s6
	s_or_b32 s4, s4, s5
	s_cmpk_lt_i32 s1, 0x80
	s_cselect_b64 s[6:7], -1, 0
	s_cmp_lt_i32 s4, 32
	s_cselect_b64 s[8:9], -1, 0
	s_and_b64 s[6:7], s[6:7], s[8:9]
	s_andn2_b64 vcc, exec, s[6:7]
	s_cbranch_vccnz .LBB0_1312
	s_lshl_b32 s8, s1, 7
	v_add_u32_e32 v102, s8, v125
	v_ashrrev_i32_e32 v103, 31, v102
	v_readlane_b32 s14, v254, 41
	v_readlane_b32 s15, v254, 42
	v_or_b32_e32 v98, 16, v102
	v_ashrrev_i32_e32 v99, 31, v98
	s_lshl_b32 s6, s4, 7
	s_mov_b32 s4, 0x358637bd
	s_mov_b32 s16, 0x3a800000
	s_mov_b32 s1, 0x800000
	v_or_b32_e32 v106, 32, v102
	v_ashrrev_i32_e32 v107, 31, v106
	v_or_b32_e32 v104, 48, v102
	v_ashrrev_i32_e32 v105, 31, v104
	s_ashr_i32 s9, s8, 31
	v_and_b32_e32 v22, 48, v148
	v_mov_b32_e32 v23, 0
	v_mov_b32_e32 v21, s4
	v_lshlrev_b64 v[0:1], 6, v[102:103]
	v_lshl_add_u64 v[0:1], s[14:15], 0, v[0:1]
	v_lshl_add_u64 v[0:1], v[22:23], 0, v[0:1]
	v_lshlrev_b64 v[2:3], 6, v[98:99]
	v_lshl_add_u64 v[2:3], s[14:15], 0, v[2:3]
	v_lshl_add_u64 v[2:3], v[22:23], 0, v[2:3]
	v_lshlrev_b64 v[4:5], 6, v[106:107]
	v_lshl_add_u64 v[4:5], s[14:15], 0, v[4:5]
	v_lshl_add_u64 v[4:5], v[22:23], 0, v[4:5]
	v_lshlrev_b64 v[6:7], 6, v[104:105]
	v_lshl_add_u64 v[6:7], s[14:15], 0, v[6:7]
	v_lshl_add_u64 v[6:7], v[22:23], 0, v[6:7]
	global_load_dwordx4 v[8:11], v[0:1], off
	global_load_dwordx4 v[12:15], v[2:3], off
	global_load_dwordx4 v[16:19], v[4:5], off
	global_load_dwordx4 v[0:3], v[6:7], off
	s_waitcnt vmcnt(0)
	v_add_f32_e32 v8, v8, v9
	v_add_f32_e32 v10, v10, v11
	v_add_f32_e32 v8, v8, v10
	v_add_f32_e32 v12, v12, v13
	v_add_f32_e32 v14, v14, v15
	v_add_f32_e32 v12, v12, v14
	v_add_f32_e32 v16, v16, v17
	v_add_f32_e32 v18, v18, v19
	v_add_f32_e32 v16, v16, v18
	v_add_f32_e32 v0, v0, v1
	v_add_f32_e32 v2, v2, v3
	v_add_f32_e32 v0, v0, v2
	v_mov_b32_e32 v9, v8
	s_nop 1
	v_permlane16_swap_b32_e32 v8, v9
	v_mov_b32_e32 v10, v8
	v_mov_b32_e32 v11, v9
	s_nop 1
	v_permlane32_swap_b32_e32 v8, v10
	v_permlane32_swap_b32_e32 v9, v11
	v_add_f32_e32 v8, v8, v9
	v_add_f32_e32 v8, v8, v10
	v_add_f32_e32 v8, v8, v11
	v_fma_f32 v8, v8, s16, v21
	v_mov_b32_e32 v13, v12
	s_nop 1
	v_permlane16_swap_b32_e32 v12, v13
	v_mov_b32_e32 v14, v12
	v_mov_b32_e32 v15, v13
	s_nop 1
	v_permlane32_swap_b32_e32 v12, v14
	v_permlane32_swap_b32_e32 v13, v15
	v_add_f32_e32 v12, v12, v13
	v_add_f32_e32 v12, v12, v14
	v_add_f32_e32 v12, v12, v15
	v_fma_f32 v12, v12, s16, v21
	v_mov_b32_e32 v17, v16
	s_nop 1
	v_permlane16_swap_b32_e32 v16, v17
	v_mov_b32_e32 v18, v16
	v_mov_b32_e32 v19, v17
	s_nop 1
	v_permlane32_swap_b32_e32 v16, v18
	v_permlane32_swap_b32_e32 v17, v19
	v_add_f32_e32 v16, v16, v17
	v_add_f32_e32 v16, v16, v18
	v_add_f32_e32 v16, v16, v19
	v_fma_f32 v16, v16, s16, v21
	v_mov_b32_e32 v1, v0
	s_nop 1
	v_permlane16_swap_b32_e32 v0, v1
	v_mov_b32_e32 v2, v0
	v_mov_b32_e32 v3, v1
	s_nop 1
	v_permlane32_swap_b32_e32 v0, v2
	v_permlane32_swap_b32_e32 v1, v3
	v_add_f32_e32 v0, v0, v1
	v_add_f32_e32 v0, v0, v2
	v_add_f32_e32 v0, v0, v3
	v_fma_f32 v0, v0, s16, v21
	v_mul_f32_e32 v9, 0x4b800000, v8
	v_cmp_gt_f32_e32 vcc, s1, v8
	s_nop 1
	v_cndmask_b32_e32 v8, v8, v9, vcc
	v_rsq_f32_e32 v8, v8
	s_nop 0
	v_mul_f32_e32 v9, 0x45800000, v8
	v_cndmask_b32_e32 v128, v8, v9, vcc
	v_mul_f32_e32 v13, 0x4b800000, v12
	v_cmp_gt_f32_e32 vcc, s1, v12
	s_nop 1
	v_cndmask_b32_e32 v12, v12, v13, vcc
	v_rsq_f32_e32 v12, v12
	s_nop 0
	v_mul_f32_e32 v13, 0x45800000, v12
	v_cndmask_b32_e32 v126, v12, v13, vcc
	v_mul_f32_e32 v17, 0x4b800000, v16
	v_cmp_gt_f32_e32 vcc, s1, v16
	s_nop 1
	v_cndmask_b32_e32 v16, v16, v17, vcc
	v_rsq_f32_e32 v16, v16
	s_nop 0
	v_mul_f32_e32 v17, 0x45800000, v16
	v_cndmask_b32_e32 v129, v16, v17, vcc
	v_mul_f32_e32 v1, 0x4b800000, v0
	v_cmp_gt_f32_e32 vcc, s1, v0
	s_nop 1
	v_cndmask_b32_e32 v0, v0, v1, vcc
	v_rsq_f32_e32 v0, v0
	s_nop 0
	v_mul_f32_e32 v1, 0x45800000, v0
	v_cndmask_b32_e32 v127, v0, v1, vcc
	v_mov_b32_e32 v72, v148
	v_or_b32_e32 v100, s6, v124
	v_ashrrev_i32_e32 v64, 3, v72
	v_ashrrev_i32_e32 v65, 31, v64
	v_and_b32_e32 v75, 48, v72
	v_lshlrev_b64 v[16:17], 11, v[64:65]
	v_lshlrev_b32_e32 v65, 4, v72
	v_and_b32_e32 v150, 0x70, v65
	v_add_u32_e32 v66, 32, v64
	s_lshl_b64 s[4:5], s[8:9], 11
	v_readlane_b32 s8, v254, 43
	v_readlane_b32 s9, v254, 44
	s_add_u32 s4, s8, s4
	s_addc_u32 s5, s9, s5
	v_lshlrev_b32_e32 v0, 3, v72
	s_ashr_i32 s7, s6, 31
	v_and_b32_e32 v74, 0x70, v0
	v_bitop3_b32 v134, v0, v75, s23 bitop3:0x6c
	v_lshl_add_u64 v[0:1], s[4:5], 0, v[16:17]
	v_add_u32_e32 v68, 64, v64
	v_add_u32_e32 v70, 0x60, v64
	s_lshl_b64 s[6:7], s[6:7], 11
	v_lshl_add_u64 v[108:109], v[0:1], 0, v[150:151]
	v_ashrrev_i32_e32 v67, 31, v66
	v_ashrrev_i32_e32 v69, 31, v68
	v_ashrrev_i32_e32 v71, 31, v70
	s_add_u32 s6, s10, s6
	v_lshlrev_b64 v[20:21], 11, v[66:67]
	v_lshlrev_b64 v[24:25], 11, v[68:69]
	v_lshlrev_b64 v[28:29], 11, v[70:71]
	s_addc_u32 s7, s11, s7
	v_lshl_add_u64 v[4:5], s[4:5], 0, v[20:21]
	v_lshl_add_u64 v[8:9], s[4:5], 0, v[24:25]
	v_lshl_add_u64 v[12:13], s[4:5], 0, v[28:29]
	v_lshl_add_u64 v[110:111], v[4:5], 0, v[150:151]
	v_lshl_add_u64 v[112:113], v[8:9], 0, v[150:151]
	v_lshl_add_u64 v[114:115], v[12:13], 0, v[150:151]
	v_lshl_add_u64 v[16:17], s[6:7], 0, v[16:17]
	v_lshl_add_u64 v[116:117], v[16:17], 0, v[150:151]
	v_lshl_add_u64 v[20:21], s[6:7], 0, v[20:21]
	v_lshl_add_u64 v[118:119], v[20:21], 0, v[150:151]
	v_lshl_add_u64 v[24:25], s[6:7], 0, v[24:25]
; DI int TIDX() { int t = threadIdx.x; asm volatile("" : "+v"(t)); return t; }
; #define GL_LOAD(s_, kt_) if (VAR != 1) { a##s_##0 = GL_A(0, kt_); a##s_##1 = GL_A(1, kt_); a##s_##2 = GL_A(2, kt_); a##s_##3 = GL_A(3, kt_); b##s_##0 = GL_B(0, kt_); b##s_##1 = GL_B(1, kt_); b##s_##2 = GL_B(2, kt_); b##s_##3 = GL_B(3, kt_); }
; #define LDS_STORE(s_, buf_) if (VAR != 2) { LDS_ST1(sA, 0, buf_, a##s_##0) LDS_ST1(sA, 1, buf_, a##s_##1) LDS_ST1(sA, 2, buf_, a##s_##2) LDS_ST1(sA, 3, buf_, a##s_##3) LDS_ST1(sB, 0, buf_, b##s_##0) LDS_ST1(sB, 1, buf_, b##s_##1) LDS_ST1(sB, 2, buf_, b##s_##2) LDS_ST1(sB, 3, buf_, b##s_##3) }
;   const int tid = TIDX(), lane = tid & 63, wid = tid >> 6, wm = wid >> 1, wn = wid & 1, lr = lane & 15, g = lane >> 4;
;   char* sA = smem; char* sB = smem + 2 * LTILE;
;   uint4 a00 = {}, a01 = {}, a02 = {}, a03 = {}, b00 = {}, b01 = {}, b02 = {}, b03 = {}, a10 = {}, a11 = {}, a12 = {}, a13 = {}, b10 = {}, b11 = {}, b12 = {}, b13 = {};
;   constexpr int nk = NK;
;   const int sw0 = (g ^ ((lr >> 1) & 7)) << 4, sw1 = sw0 ^ 64;
;   const int r0 = tid >> 3, kc = tid & 7, kcs = kc ^ ((r0 >> 1) & 7);
;     ...
;   GL_LOAD(0, 0)
;   GL_LOAD(1, 1)
;   LDS_STORE(0, 0)
;   if (VAR != 4) __syncthreads();
; #pragma unroll
;   for (int kt = 0; kt < nk; kt += 2) {
;     if (kt + 2 < nk) { GL_LOAD(0, kt + 2) }
;     MMA_TILE(0)
	v_lshl_add_u64 v[120:121], v[24:25], 0, v[150:151]
	v_lshl_add_u64 v[28:29], s[6:7], 0, v[28:29]
	v_lshl_add_u64 v[122:123], v[28:29], 0, v[150:151]
	v_bitop3_b32 v65, v65, s23, v72 bitop3:0x48
	v_lshl_or_b32 v101, v64, 7, v65
	v_and_b32_e32 v73, 15, v72
	v_lshl_or_b32 v131, v66, 7, v65
	v_lshl_or_b32 v132, v68, 7, v65
	v_lshl_or_b32 v130, v70, 7, v65
	v_xor_b32_e32 v135, 64, v134
	v_writelane_b32 v255, s60, 0
	v_writelane_b32 v255, s61, 1
	v_writelane_b32 v255, s62, 2
	v_writelane_b32 v255, s63, 3
	v_writelane_b32 v255, s64, 4
	v_writelane_b32 v255, s65, 5
	v_writelane_b32 v255, s66, 6
	v_writelane_b32 v255, s67, 7
	v_writelane_b32 v255, s68, 8
	v_writelane_b32 v255, s69, 9
	v_writelane_b32 v255, s70, 10
	v_writelane_b32 v255, s71, 11
	v_writelane_b32 v255, s72, 12
	v_writelane_b32 v255, s73, 13
	v_writelane_b32 v255, s74, 14
	v_writelane_b32 v255, s75, 15
	v_mov_b32_e32 v3, v101
	v_and_b32_e32 v3, 0xffffff80, v3
	s_nop 0
	v_readfirstlane_b32 s60, v3
	v_add_u32_e32 v3, 0x4000, v101
	v_and_b32_e32 v3, 0xffffff80, v3
	s_nop 0
	v_readfirstlane_b32 s61, v3
	v_add_u32_e32 v3, 0x8000, v101
	v_and_b32_e32 v3, 0xffffff80, v3
	s_nop 0
	v_readfirstlane_b32 s62, v3
	v_add_u32_e32 v3, 0xc000, v101
	v_and_b32_e32 v3, 0xffffff80, v3
	s_nop 0
	v_readfirstlane_b32 s63, v3
	v_mov_b32_e32 v3, v130
	v_and_b32_e32 v3, 0xffffff80, v3
	s_nop 0
	v_readfirstlane_b32 s64, v3
	v_add_u32_e32 v3, 0x4000, v130
	v_and_b32_e32 v3, 0xffffff80, v3
	s_nop 0
	v_readfirstlane_b32 s65, v3
	v_add_u32_e32 v3, 0x8000, v130
	v_and_b32_e32 v3, 0xffffff80, v3
	s_nop 0
	v_readfirstlane_b32 s66, v3
	v_add_u32_e32 v3, 0xc000, v130
	v_and_b32_e32 v3, 0xffffff80, v3
	s_nop 0
	v_readfirstlane_b32 s67, v3
	v_mov_b32_e32 v3, v131
	v_and_b32_e32 v3, 0xffffff80, v3
	s_nop 0
	v_readfirstlane_b32 s68, v3
	v_add_u32_e32 v3, 0x4000, v131
	v_and_b32_e32 v3, 0xffffff80, v3
	s_nop 0
	v_readfirstlane_b32 s69, v3
	v_add_u32_e32 v3, 0x8000, v131
	v_and_b32_e32 v3, 0xffffff80, v3
	s_nop 0
	v_readfirstlane_b32 s70, v3
	v_add_u32_e32 v3, 0xc000, v131
	v_and_b32_e32 v3, 0xffffff80, v3
	s_nop 0
	v_readfirstlane_b32 s71, v3
	v_mov_b32_e32 v3, v132
	v_and_b32_e32 v3, 0xffffff80, v3
	s_nop 0
	v_readfirstlane_b32 s72, v3
	v_add_u32_e32 v3, 0x4000, v132
	v_and_b32_e32 v3, 0xffffff80, v3
	s_nop 0
	v_readfirstlane_b32 s73, v3
	v_add_u32_e32 v3, 0x8000, v132
	v_and_b32_e32 v3, 0xffffff80, v3
	s_nop 0
	v_readfirstlane_b32 s74, v3
	v_add_u32_e32 v3, 0xc000, v132
	v_and_b32_e32 v3, 0xffffff80, v3
	s_nop 0
	v_readfirstlane_b32 s75, v3
	v_and_b32_e32 v30, 7, v148
	v_bfe_u32 v31, v148, 4, 3
	v_xor_b32_e32 v31, v31, v30
	v_sub_u32_e32 v31, v31, v30
	v_lshlrev_b32_e32 v30, 4, v31
	v_ashrrev_i32_e32 v31, 31, v30
	v_lshl_add_u64 v[0:1], v[108:109], 0, v[30:31]
	s_mov_b32 m0, s60
	s_nop 0
	global_load_lds_dwordx4 v[0:1], off
	v_lshrrev_b32_e32 v0, 1, v72
	v_and_or_b32 v0, v0, s24, v73
	v_lshlrev_b32_e32 v137, 7, v0
	v_lshlrev_b32_e32 v0, 7, v72
	v_and_b32_e32 v146, 0x2780, v0
	v_bitop3_b32 v133, v137, v74, v75 bitop3:0xf6
	v_or_b32_e32 v136, v146, v134
	v_bitop3_b32 v134, v137, v134, 64 bitop3:0xf6
	v_or_b32_e32 v135, v146, v135
	v_lshl_add_u64 v[4:5], v[110:111], 0, v[30:31]
	s_mov_b32 m0, s68
	s_nop 0
	global_load_lds_dwordx4 v[4:5], off
	v_lshl_add_u64 v[8:9], v[112:113], 0, v[30:31]
	s_mov_b32 m0, s72
	s_nop 0
	global_load_lds_dwordx4 v[8:9], off
	v_lshl_add_u64 v[12:13], v[114:115], 0, v[30:31]
	s_mov_b32 m0, s64
	s_nop 0
	global_load_lds_dwordx4 v[12:13], off
	v_lshl_add_u64 v[16:17], v[116:117], 0, v[30:31]
	s_mov_b32 m0, s62
	s_nop 0
	global_load_lds_dwordx4 v[16:17], off
	v_lshl_add_u64 v[20:21], v[118:119], 0, v[30:31]
	s_mov_b32 m0, s70
	s_nop 0
	global_load_lds_dwordx4 v[20:21], off
	v_lshl_add_u64 v[24:25], v[120:121], 0, v[30:31]
	s_mov_b32 m0, s74
	s_nop 0
	global_load_lds_dwordx4 v[24:25], off
	v_lshl_add_u64 v[28:29], v[122:123], 0, v[30:31]
	s_mov_b32 m0, s66
	s_nop 0
	global_load_lds_dwordx4 v[28:29], off
	s_waitcnt lgkmcnt(0)
	s_waitcnt vmcnt(0)
	s_barrier
	s_setprio 1
	ds_read_b128 v[64:67], v133
	ds_read_b128 v[68:71], v136 offset:32768
	s_waitcnt lgkmcnt(0)
	v_mfma_f32_16x16x32_f16 v[138:141], v[68:71], v[64:67], 0
	ds_read_b128 v[72:75], v133 offset:2048
	ds_read_b128 v[76:79], v136 offset:34816
	s_waitcnt lgkmcnt(1)
	v_mfma_f32_16x16x32_f16 v[158:161], v[68:71], v[72:75], 0
	ds_read_b128 v[80:83], v133 offset:4096
	ds_read_b128 v[84:87], v136 offset:36864
	s_waitcnt lgkmcnt(2)
	v_mfma_f32_16x16x32_f16 v[142:145], v[76:79], v[64:67], 0
	ds_read_b128 v[88:91], v133 offset:6144
	ds_read_b128 v[92:95], v136 offset:38912
	v_mfma_f32_16x16x32_f16 v[162:165], v[76:79], v[72:75], 0
	ds_read_b128 v[202:205], v135 offset:32768
	ds_read_b128 v[206:209], v134 offset:2048
	s_waitcnt lgkmcnt(5)
	v_mfma_f32_16x16x32_f16 v[190:193], v[68:71], v[80:83], 0
	ds_read_b128 v[210:213], v135 offset:34816
	ds_read_b128 v[220:223], v134 offset:4096
	s_waitcnt lgkmcnt(5)
	v_mfma_f32_16x16x32_f16 v[68:71], v[68:71], v[88:91], 0
	ds_read_b128 v[224:227], v135 offset:36864
	v_mfma_f32_16x16x32_f16 v[194:197], v[76:79], v[80:83], 0
	ds_read_b128 v[228:231], v134 offset:6144
	v_mfma_f32_16x16x32_f16 v[76:79], v[76:79], v[88:91], 0
	ds_read_b128 v[232:235], v135 offset:38912
	v_mfma_f32_16x16x32_f16 v[154:157], v[84:87], v[64:67], 0
	v_mfma_f32_16x16x32_f16 v[166:169], v[84:87], v[72:75], 0
	s_waitcnt lgkmcnt(7)
	v_mfma_f32_16x16x32_f16 v[64:67], v[92:95], v[64:67], 0
	v_mfma_f32_16x16x32_f16 v[72:75], v[92:95], v[72:75], 0
	v_mfma_f32_16x16x32_f16 v[198:201], v[84:87], v[80:83], 0
	v_and_b32_e32 v62, 7, v148
	v_bfe_u32 v63, v148, 4, 3
	v_xor_b32_e32 v63, v63, v62
	v_sub_u32_e32 v63, v63, v62
	v_lshlrev_b32_e32 v62, 4, v63
	v_add_u32_e32 v62, 0x80, v62
	v_ashrrev_i32_e32 v63, 31, v62
	v_mfma_f32_16x16x32_f16 v[84:87], v[84:87], v[88:91], 0
	v_lshl_add_u64 v[32:33], v[108:109], 0, v[62:63]
	s_mov_b32 m0, s61
	s_nop 0
	global_load_lds_dwordx4 v[32:33], off
	v_lshl_add_u64 v[36:37], v[110:111], 0, v[62:63]
	s_mov_b32 m0, s69
	s_nop 0
	global_load_lds_dwordx4 v[36:37], off
	v_mfma_f32_16x16x32_f16 v[80:83], v[92:95], v[80:83], 0
	v_lshl_add_u64 v[40:41], v[112:113], 0, v[62:63]
	s_mov_b32 m0, s73
	s_nop 0
	global_load_lds_dwordx4 v[40:41], off
	v_lshl_add_u64 v[44:45], v[114:115], 0, v[62:63]
	s_mov_b32 m0, s65
	s_nop 0
	global_load_lds_dwordx4 v[44:45], off
	v_mfma_f32_16x16x32_f16 v[88:91], v[92:95], v[88:91], 0
	ds_read_b128 v[92:95], v134
	v_lshl_add_u64 v[48:49], v[116:117], 0, v[62:63]
	s_mov_b32 m0, s63
	s_nop 0
	global_load_lds_dwordx4 v[48:49], off
	v_lshl_add_u64 v[52:53], v[118:119], 0, v[62:63]
	s_mov_b32 m0, s71
	s_nop 0
	global_load_lds_dwordx4 v[52:53], off
	v_lshl_add_u64 v[56:57], v[120:121], 0, v[62:63]
	s_mov_b32 m0, s75
	s_nop 0
	global_load_lds_dwordx4 v[56:57], off
	v_lshl_add_u64 v[60:61], v[122:123], 0, v[62:63]
	s_mov_b32 m0, s67
	s_nop 0
	global_load_lds_dwordx4 v[60:61], off
	s_waitcnt vmcnt(0) lgkmcnt(0)
	s_barrier
; #define GL_LOAD(s_, kt_) if (VAR != 1) { a##s_##0 = GL_A(0, kt_); a##s_##1 = GL_A(1, kt_); a##s_##2 = GL_A(2, kt_); a##s_##3 = GL_A(3, kt_); b##s_##0 = GL_B(0, kt_); b##s_##1 = GL_B(1, kt_); b##s_##2 = GL_B(2, kt_); b##s_##3 = GL_B(3, kt_); }
; #define LDS_STORE(s_, buf_) if (VAR != 2) { LDS_ST1(sA, 0, buf_, a##s_##0) LDS_ST1(sA, 1, buf_, a##s_##1) LDS_ST1(sA, 2, buf_, a##s_##2) LDS_ST1(sA, 3, buf_, a##s_##3) LDS_ST1(sB, 0, buf_, b##s_##0) LDS_ST1(sB, 1, buf_, b##s_##1) LDS_ST1(sB, 2, buf_, b##s_##2) LDS_ST1(sB, 3, buf_, b##s_##3) }
;     ...
;   GL_LOAD(0, 0)
;   GL_LOAD(1, 1)
;   LDS_STORE(0, 0)
;   if (VAR != 4) __syncthreads();
; #pragma unroll
;   for (int kt = 0; kt < nk; kt += 2) {
;     if (kt + 2 < nk) { GL_LOAD(0, kt + 2) }
;     MMA_TILE(0)
;     LDS_STORE(1, 1)
;     if (VAR != 4) __syncthreads();
;     if (kt + 3 < nk) { GL_LOAD(1, kt + 3) }
;     MMA_TILE(1)
;     if (kt + 2 < nk) { LDS_STORE(0, 0) }
;     if (VAR != 4) __syncthreads();
	v_mfma_f32_16x16x32_f16 v[138:141], v[202:205], v[92:95], v[138:141]
	v_mfma_f32_16x16x32_f16 v[142:145], v[210:213], v[92:95], v[142:145]
	v_mfma_f32_16x16x32_f16 v[154:157], v[224:227], v[92:95], v[154:157]
	v_mfma_f32_16x16x32_f16 v[64:67], v[232:235], v[92:95], v[64:67]
	v_mfma_f32_16x16x32_f16 v[92:95], v[202:205], v[206:209], v[158:161]
	v_mfma_f32_16x16x32_f16 v[158:161], v[210:213], v[206:209], v[162:165]
	v_mfma_f32_16x16x32_f16 v[162:165], v[224:227], v[206:209], v[166:169]
	v_mfma_f32_16x16x32_f16 v[166:169], v[202:205], v[220:223], v[190:193]
	v_mfma_f32_16x16x32_f16 v[68:71], v[202:205], v[228:231], v[68:71]
	ds_read_b128 v[202:205], v136 offset:49152
	v_mfma_f32_16x16x32_f16 v[190:193], v[210:213], v[220:223], v[194:197]
	v_mfma_f32_16x16x32_f16 v[76:79], v[210:213], v[228:231], v[76:79]
	ds_read_b128 v[210:213], v136 offset:51200
	v_and_b32_e32 v30, 7, v148
	v_bfe_u32 v31, v148, 4, 3
	v_xor_b32_e32 v31, v31, v30
	v_sub_u32_e32 v31, v31, v30
	v_lshlrev_b32_e32 v30, 4, v31
	v_add_u32_e32 v30, 0x100, v30
	v_ashrrev_i32_e32 v31, 31, v30
	v_mfma_f32_16x16x32_f16 v[72:75], v[232:235], v[206:209], v[72:75]
	ds_read_b128 v[206:209], v133 offset:18432
	v_mfma_f32_16x16x32_f16 v[194:197], v[224:227], v[220:223], v[198:201]
	s_nop 2
	ds_read_b128 v[198:201], v133 offset:16384
	v_mfma_f32_16x16x32_f16 v[84:87], v[224:227], v[228:231], v[84:87]
	ds_read_b128 v[224:227], v136 offset:53248
	v_mfma_f32_16x16x32_f16 v[80:83], v[232:235], v[220:223], v[80:83]
	ds_read_b128 v[220:223], v133 offset:20480
	v_mfma_f32_16x16x32_f16 v[88:91], v[232:235], v[228:231], v[88:91]
	ds_read_b128 v[228:231], v133 offset:22528
	s_waitcnt lgkmcnt(3)
	v_mfma_f32_16x16x32_f16 v[138:141], v[202:205], v[198:201], v[138:141]
	ds_read_b128 v[232:235], v136 offset:55296
	v_mfma_f32_16x16x32_f16 v[92:95], v[202:205], v[206:209], v[92:95]
	v_lshl_add_u64 v[0:1], v[108:109], 0, v[30:31]
	s_mov_b32 m0, s60
	s_nop 0
	global_load_lds_dwordx4 v[0:1], off
	v_mfma_f32_16x16x32_f16 v[142:145], v[210:213], v[198:201], v[142:145]
	v_lshl_add_u64 v[4:5], v[110:111], 0, v[30:31]
	s_mov_b32 m0, s68
	s_nop 0
	global_load_lds_dwordx4 v[4:5], off
	v_mfma_f32_16x16x32_f16 v[158:161], v[210:213], v[206:209], v[158:161]
	v_lshl_add_u64 v[8:9], v[112:113], 0, v[30:31]
	s_mov_b32 m0, s72
	s_nop 0
	global_load_lds_dwordx4 v[8:9], off
	s_waitcnt lgkmcnt(2)
	v_mfma_f32_16x16x32_f16 v[166:169], v[202:205], v[220:223], v[166:169]
	v_lshl_add_u64 v[12:13], v[114:115], 0, v[30:31]
	s_mov_b32 m0, s64
	s_nop 0
	global_load_lds_dwordx4 v[12:13], off
	s_waitcnt lgkmcnt(1)
	v_mfma_f32_16x16x32_f16 v[68:71], v[202:205], v[228:231], v[68:71]
	ds_read_b128 v[202:205], v135 offset:49152
	v_mfma_f32_16x16x32_f16 v[190:193], v[210:213], v[220:223], v[190:193]
	v_lshl_add_u64 v[16:17], v[116:117], 0, v[30:31]
	s_mov_b32 m0, s62
	s_nop 0
	global_load_lds_dwordx4 v[16:17], off
	v_mfma_f32_16x16x32_f16 v[76:79], v[210:213], v[228:231], v[76:79]
	ds_read_b128 v[210:213], v135 offset:51200
	v_mfma_f32_16x16x32_f16 v[154:157], v[224:227], v[198:201], v[154:157]
	v_lshl_add_u64 v[20:21], v[118:119], 0, v[30:31]
	s_mov_b32 m0, s70
	s_nop 0
	global_load_lds_dwordx4 v[20:21], off
	v_mfma_f32_16x16x32_f16 v[162:165], v[224:227], v[206:209], v[162:165]
	v_lshl_add_u64 v[24:25], v[120:121], 0, v[30:31]
	s_mov_b32 m0, s74
	s_nop 0
	global_load_lds_dwordx4 v[24:25], off
	s_waitcnt lgkmcnt(2)
	v_mfma_f32_16x16x32_f16 v[64:67], v[232:235], v[198:201], v[64:67]
	ds_read_b128 v[198:201], v134 offset:16384
	v_mfma_f32_16x16x32_f16 v[72:75], v[232:235], v[206:209], v[72:75]
	ds_read_b128 v[206:209], v134 offset:18432
	v_mfma_f32_16x16x32_f16 v[194:197], v[224:227], v[220:223], v[194:197]
	v_lshl_add_u64 v[28:29], v[122:123], 0, v[30:31]
	s_mov_b32 m0, s66
	s_nop 0
	global_load_lds_dwordx4 v[28:29], off
	v_mfma_f32_16x16x32_f16 v[84:87], v[224:227], v[228:231], v[84:87]
	ds_read_b128 v[224:227], v135 offset:53248
	v_mfma_f32_16x16x32_f16 v[80:83], v[232:235], v[220:223], v[80:83]
	ds_read_b128 v[220:223], v134 offset:20480
	v_mfma_f32_16x16x32_f16 v[88:91], v[232:235], v[228:231], v[88:91]
	ds_read_b128 v[228:231], v134 offset:22528
	ds_read_b128 v[232:235], v135 offset:55296
	s_waitcnt vmcnt(0) lgkmcnt(0)
	s_barrier
	v_mfma_f32_16x16x32_f16 v[138:141], v[202:205], v[198:201], v[138:141]
	v_mfma_f32_16x16x32_f16 v[92:95], v[202:205], v[206:209], v[92:95]
	v_mfma_f32_16x16x32_f16 v[142:145], v[210:213], v[198:201], v[142:145]
	v_mfma_f32_16x16x32_f16 v[158:161], v[210:213], v[206:209], v[158:161]
	v_mfma_f32_16x16x32_f16 v[166:169], v[202:205], v[220:223], v[166:169]
	v_mfma_f32_16x16x32_f16 v[68:71], v[202:205], v[228:231], v[68:71]
	ds_read_b128 v[202:205], v136 offset:32768
	v_mfma_f32_16x16x32_f16 v[190:193], v[210:213], v[220:223], v[190:193]
	v_mfma_f32_16x16x32_f16 v[76:79], v[210:213], v[228:231], v[76:79]
	ds_read_b128 v[210:213], v136 offset:34816
	v_mfma_f32_16x16x32_f16 v[154:157], v[224:227], v[198:201], v[154:157]
	v_mfma_f32_16x16x32_f16 v[162:165], v[224:227], v[206:209], v[162:165]
	v_mfma_f32_16x16x32_f16 v[64:67], v[232:235], v[198:201], v[64:67]
	ds_read_b128 v[198:201], v133
	v_mfma_f32_16x16x32_f16 v[72:75], v[232:235], v[206:209], v[72:75]
	ds_read_b128 v[206:209], v133 offset:2048
	v_mfma_f32_16x16x32_f16 v[194:197], v[224:227], v[220:223], v[194:197]
	v_and_b32_e32 v62, 7, v148
	v_bfe_u32 v63, v148, 4, 3
	v_xor_b32_e32 v63, v63, v62
	v_sub_u32_e32 v63, v63, v62
	v_lshlrev_b32_e32 v62, 4, v63
	v_add_u32_e32 v62, 0x180, v62
	v_ashrrev_i32_e32 v63, 31, v62
	v_mfma_f32_16x16x32_f16 v[84:87], v[224:227], v[228:231], v[84:87]
	ds_read_b128 v[224:227], v136 offset:36864
	v_mfma_f32_16x16x32_f16 v[80:83], v[232:235], v[220:223], v[80:83]
	ds_read_b128 v[220:223], v133 offset:4096
	v_mfma_f32_16x16x32_f16 v[88:91], v[232:235], v[228:231], v[88:91]
	ds_read_b128 v[228:231], v133 offset:6144
	s_waitcnt lgkmcnt(4)
; #define GL_LOAD(s_, kt_) if (VAR != 1) { a##s_##0 = GL_A(0, kt_); a##s_##1 = GL_A(1, kt_); a##s_##2 = GL_A(2, kt_); a##s_##3 = GL_A(3, kt_); b##s_##0 = GL_B(0, kt_); b##s_##1 = GL_B(1, kt_); b##s_##2 = GL_B(2, kt_); b##s_##3 = GL_B(3, kt_); }
; #define LDS_STORE(s_, buf_) if (VAR != 2) { LDS_ST1(sA, 0, buf_, a##s_##0) LDS_ST1(sA, 1, buf_, a##s_##1) LDS_ST1(sA, 2, buf_, a##s_##2) LDS_ST1(sA, 3, buf_, a##s_##3) LDS_ST1(sB, 0, buf_, b##s_##0) LDS_ST1(sB, 1, buf_, b##s_##1) LDS_ST1(sB, 2, buf_, b##s_##2) LDS_ST1(sB, 3, buf_, b##s_##3) }
;     ...
;   GL_LOAD(0, 0)
;   GL_LOAD(1, 1)
;   LDS_STORE(0, 0)
;   if (VAR != 4) __syncthreads();
; #pragma unroll
;   for (int kt = 0; kt < nk; kt += 2) {
;     if (kt + 2 < nk) { GL_LOAD(0, kt + 2) }
;     MMA_TILE(0)
;     LDS_STORE(1, 1)
;     if (VAR != 4) __syncthreads();
;     if (kt + 3 < nk) { GL_LOAD(1, kt + 3) }
;     MMA_TILE(1)
;     if (kt + 2 < nk) { LDS_STORE(0, 0) }
;     if (VAR != 4) __syncthreads();
	v_mfma_f32_16x16x32_f16 v[138:141], v[202:205], v[198:201], v[138:141]
	ds_read_b128 v[232:235], v136 offset:38912
	s_waitcnt lgkmcnt(4)
	v_mfma_f32_16x16x32_f16 v[92:95], v[202:205], v[206:209], v[92:95]
	v_lshl_add_u64 v[32:33], v[108:109], 0, v[62:63]
	s_mov_b32 m0, s61
	s_nop 0
	global_load_lds_dwordx4 v[32:33], off
	v_mfma_f32_16x16x32_f16 v[142:145], v[210:213], v[198:201], v[142:145]
	v_lshl_add_u64 v[36:37], v[110:111], 0, v[62:63]
	s_mov_b32 m0, s69
	s_nop 0
	global_load_lds_dwordx4 v[36:37], off
	v_mfma_f32_16x16x32_f16 v[158:161], v[210:213], v[206:209], v[158:161]
	v_lshl_add_u64 v[40:41], v[112:113], 0, v[62:63]
	s_mov_b32 m0, s73
	s_nop 0
	global_load_lds_dwordx4 v[40:41], off
	s_waitcnt lgkmcnt(2)
	v_mfma_f32_16x16x32_f16 v[166:169], v[202:205], v[220:223], v[166:169]
	v_lshl_add_u64 v[44:45], v[114:115], 0, v[62:63]
	s_mov_b32 m0, s65
	s_nop 0
	global_load_lds_dwordx4 v[44:45], off
	s_waitcnt lgkmcnt(1)
	v_mfma_f32_16x16x32_f16 v[68:71], v[202:205], v[228:231], v[68:71]
	ds_read_b128 v[202:205], v135 offset:32768
	v_mfma_f32_16x16x32_f16 v[190:193], v[210:213], v[220:223], v[190:193]
	v_lshl_add_u64 v[48:49], v[116:117], 0, v[62:63]
	s_mov_b32 m0, s63
	s_nop 0
	global_load_lds_dwordx4 v[48:49], off
	v_mfma_f32_16x16x32_f16 v[76:79], v[210:213], v[228:231], v[76:79]
	ds_read_b128 v[210:213], v135 offset:34816
	v_mfma_f32_16x16x32_f16 v[154:157], v[224:227], v[198:201], v[154:157]
	v_lshl_add_u64 v[52:53], v[118:119], 0, v[62:63]
	s_mov_b32 m0, s71
	s_nop 0
	global_load_lds_dwordx4 v[52:53], off
	v_mfma_f32_16x16x32_f16 v[162:165], v[224:227], v[206:209], v[162:165]
	v_lshl_add_u64 v[56:57], v[120:121], 0, v[62:63]
	s_mov_b32 m0, s75
	s_nop 0
	global_load_lds_dwordx4 v[56:57], off
	s_waitcnt lgkmcnt(2)
	v_mfma_f32_16x16x32_f16 v[64:67], v[232:235], v[198:201], v[64:67]
	ds_read_b128 v[198:201], v134
	v_mfma_f32_16x16x32_f16 v[72:75], v[232:235], v[206:209], v[72:75]
	ds_read_b128 v[206:209], v134 offset:2048
	v_mfma_f32_16x16x32_f16 v[194:197], v[224:227], v[220:223], v[194:197]
	v_lshl_add_u64 v[60:61], v[122:123], 0, v[62:63]
	s_mov_b32 m0, s67
	s_nop 0
	global_load_lds_dwordx4 v[60:61], off
	v_mfma_f32_16x16x32_f16 v[84:87], v[224:227], v[228:231], v[84:87]
	ds_read_b128 v[224:227], v135 offset:36864
	v_mfma_f32_16x16x32_f16 v[80:83], v[232:235], v[220:223], v[80:83]
	ds_read_b128 v[220:223], v134 offset:4096
	v_mfma_f32_16x16x32_f16 v[88:91], v[232:235], v[228:231], v[88:91]
	ds_read_b128 v[228:231], v134 offset:6144
	ds_read_b128 v[232:235], v135 offset:38912
	s_waitcnt vmcnt(0) lgkmcnt(0)
	s_barrier
	v_mfma_f32_16x16x32_f16 v[138:141], v[202:205], v[198:201], v[138:141]
	v_mfma_f32_16x16x32_f16 v[92:95], v[202:205], v[206:209], v[92:95]
	v_mfma_f32_16x16x32_f16 v[142:145], v[210:213], v[198:201], v[142:145]
	v_mfma_f32_16x16x32_f16 v[158:161], v[210:213], v[206:209], v[158:161]
	v_mfma_f32_16x16x32_f16 v[166:169], v[202:205], v[220:223], v[166:169]
	v_mfma_f32_16x16x32_f16 v[68:71], v[202:205], v[228:231], v[68:71]
	ds_read_b128 v[202:205], v136 offset:49152
	v_mfma_f32_16x16x32_f16 v[190:193], v[210:213], v[220:223], v[190:193]
	v_mfma_f32_16x16x32_f16 v[76:79], v[210:213], v[228:231], v[76:79]
	ds_read_b128 v[210:213], v136 offset:51200
	v_mfma_f32_16x16x32_f16 v[154:157], v[224:227], v[198:201], v[154:157]
	v_mfma_f32_16x16x32_f16 v[162:165], v[224:227], v[206:209], v[162:165]
	v_mfma_f32_16x16x32_f16 v[64:67], v[232:235], v[198:201], v[64:67]
	ds_read_b128 v[198:201], v133 offset:16384
	v_mfma_f32_16x16x32_f16 v[72:75], v[232:235], v[206:209], v[72:75]
	ds_read_b128 v[206:209], v133 offset:18432
	v_mfma_f32_16x16x32_f16 v[194:197], v[224:227], v[220:223], v[194:197]
	v_and_b32_e32 v30, 7, v148
	v_bfe_u32 v31, v148, 4, 3
	v_xor_b32_e32 v31, v31, v30
	v_sub_u32_e32 v31, v31, v30
	v_lshlrev_b32_e32 v30, 4, v31
	v_add_u32_e32 v30, 0x200, v30
	v_ashrrev_i32_e32 v31, 31, v30
	v_mfma_f32_16x16x32_f16 v[84:87], v[224:227], v[228:231], v[84:87]
	ds_read_b128 v[224:227], v136 offset:53248
	v_mfma_f32_16x16x32_f16 v[80:83], v[232:235], v[220:223], v[80:83]
	ds_read_b128 v[220:223], v133 offset:20480
	v_mfma_f32_16x16x32_f16 v[88:91], v[232:235], v[228:231], v[88:91]
	ds_read_b128 v[228:231], v133 offset:22528
	s_waitcnt lgkmcnt(4)
	v_mfma_f32_16x16x32_f16 v[138:141], v[202:205], v[198:201], v[138:141]
	ds_read_b128 v[232:235], v136 offset:55296
	s_waitcnt lgkmcnt(4)
	v_mfma_f32_16x16x32_f16 v[92:95], v[202:205], v[206:209], v[92:95]
	v_lshl_add_u64 v[0:1], v[108:109], 0, v[30:31]
	s_mov_b32 m0, s60
	s_nop 0
	global_load_lds_dwordx4 v[0:1], off
	v_mfma_f32_16x16x32_f16 v[142:145], v[210:213], v[198:201], v[142:145]
	v_lshl_add_u64 v[4:5], v[110:111], 0, v[30:31]
	s_mov_b32 m0, s68
	s_nop 0
	global_load_lds_dwordx4 v[4:5], off
	v_mfma_f32_16x16x32_f16 v[158:161], v[210:213], v[206:209], v[158:161]
	v_lshl_add_u64 v[8:9], v[112:113], 0, v[30:31]
	s_mov_b32 m0, s72
	s_nop 0
	global_load_lds_dwordx4 v[8:9], off
	s_waitcnt lgkmcnt(2)
	v_mfma_f32_16x16x32_f16 v[166:169], v[202:205], v[220:223], v[166:169]
	v_lshl_add_u64 v[12:13], v[114:115], 0, v[30:31]
	s_mov_b32 m0, s64
	s_nop 0
	global_load_lds_dwordx4 v[12:13], off
	s_waitcnt lgkmcnt(1)
	v_mfma_f32_16x16x32_f16 v[68:71], v[202:205], v[228:231], v[68:71]
	ds_read_b128 v[202:205], v135 offset:49152
	v_mfma_f32_16x16x32_f16 v[190:193], v[210:213], v[220:223], v[190:193]
	v_lshl_add_u64 v[16:17], v[116:117], 0, v[30:31]
	s_mov_b32 m0, s62
	s_nop 0
	global_load_lds_dwordx4 v[16:17], off
	v_mfma_f32_16x16x32_f16 v[76:79], v[210:213], v[228:231], v[76:79]
	ds_read_b128 v[210:213], v135 offset:51200
	v_mfma_f32_16x16x32_f16 v[154:157], v[224:227], v[198:201], v[154:157]
	v_lshl_add_u64 v[20:21], v[118:119], 0, v[30:31]
	s_mov_b32 m0, s70
	s_nop 0
	global_load_lds_dwordx4 v[20:21], off
	v_mfma_f32_16x16x32_f16 v[162:165], v[224:227], v[206:209], v[162:165]
	v_lshl_add_u64 v[24:25], v[120:121], 0, v[30:31]
	s_mov_b32 m0, s74
	s_nop 0
	global_load_lds_dwordx4 v[24:25], off
	s_waitcnt lgkmcnt(2)
	v_mfma_f32_16x16x32_f16 v[64:67], v[232:235], v[198:201], v[64:67]
	ds_read_b128 v[198:201], v134 offset:16384
	v_mfma_f32_16x16x32_f16 v[72:75], v[232:235], v[206:209], v[72:75]
	ds_read_b128 v[206:209], v134 offset:18432
	v_mfma_f32_16x16x32_f16 v[194:197], v[224:227], v[220:223], v[194:197]
	v_lshl_add_u64 v[28:29], v[122:123], 0, v[30:31]
	s_mov_b32 m0, s66
	s_nop 0
	global_load_lds_dwordx4 v[28:29], off
	v_mfma_f32_16x16x32_f16 v[84:87], v[224:227], v[228:231], v[84:87]
	ds_read_b128 v[224:227], v135 offset:53248
	v_mfma_f32_16x16x32_f16 v[80:83], v[232:235], v[220:223], v[80:83]
	ds_read_b128 v[220:223], v134 offset:20480
	v_mfma_f32_16x16x32_f16 v[88:91], v[232:235], v[228:231], v[88:91]
	ds_read_b128 v[228:231], v134 offset:22528
	ds_read_b128 v[232:235], v135 offset:55296
	s_waitcnt vmcnt(0) lgkmcnt(0)
	s_barrier
; #define GL_LOAD(s_, kt_) if (VAR != 1) { a##s_##0 = GL_A(0, kt_); a##s_##1 = GL_A(1, kt_); a##s_##2 = GL_A(2, kt_); a##s_##3 = GL_A(3, kt_); b##s_##0 = GL_B(0, kt_); b##s_##1 = GL_B(1, kt_); b##s_##2 = GL_B(2, kt_); b##s_##3 = GL_B(3, kt_); }
; #define LDS_STORE(s_, buf_) if (VAR != 2) { LDS_ST1(sA, 0, buf_, a##s_##0) LDS_ST1(sA, 1, buf_, a##s_##1) LDS_ST1(sA, 2, buf_, a##s_##2) LDS_ST1(sA, 3, buf_, a##s_##3) LDS_ST1(sB, 0, buf_, b##s_##0) LDS_ST1(sB, 1, buf_, b##s_##1) LDS_ST1(sB, 2, buf_, b##s_##2) LDS_ST1(sB, 3, buf_, b##s_##3) }
;     ...
;   GL_LOAD(0, 0)
;   GL_LOAD(1, 1)
;   LDS_STORE(0, 0)
;   if (VAR != 4) __syncthreads();
; #pragma unroll
;   for (int kt = 0; kt < nk; kt += 2) {
;     if (kt + 2 < nk) { GL_LOAD(0, kt + 2) }
;     MMA_TILE(0)
;     LDS_STORE(1, 1)
;     if (VAR != 4) __syncthreads();
;     if (kt + 3 < nk) { GL_LOAD(1, kt + 3) }
;     MMA_TILE(1)
;     if (kt + 2 < nk) { LDS_STORE(0, 0) }
;     if (VAR != 4) __syncthreads();
	v_mfma_f32_16x16x32_f16 v[138:141], v[202:205], v[198:201], v[138:141]
	v_mfma_f32_16x16x32_f16 v[92:95], v[202:205], v[206:209], v[92:95]
	v_mfma_f32_16x16x32_f16 v[142:145], v[210:213], v[198:201], v[142:145]
	v_mfma_f32_16x16x32_f16 v[158:161], v[210:213], v[206:209], v[158:161]
	v_mfma_f32_16x16x32_f16 v[166:169], v[202:205], v[220:223], v[166:169]
	v_mfma_f32_16x16x32_f16 v[68:71], v[202:205], v[228:231], v[68:71]
	ds_read_b128 v[202:205], v136 offset:32768
	v_mfma_f32_16x16x32_f16 v[190:193], v[210:213], v[220:223], v[190:193]
	v_mfma_f32_16x16x32_f16 v[76:79], v[210:213], v[228:231], v[76:79]
	ds_read_b128 v[210:213], v136 offset:34816
	v_mfma_f32_16x16x32_f16 v[154:157], v[224:227], v[198:201], v[154:157]
	v_mfma_f32_16x16x32_f16 v[162:165], v[224:227], v[206:209], v[162:165]
	v_mfma_f32_16x16x32_f16 v[64:67], v[232:235], v[198:201], v[64:67]
	ds_read_b128 v[198:201], v133
	v_mfma_f32_16x16x32_f16 v[72:75], v[232:235], v[206:209], v[72:75]
	ds_read_b128 v[206:209], v133 offset:2048
	v_mfma_f32_16x16x32_f16 v[194:197], v[224:227], v[220:223], v[194:197]
	v_and_b32_e32 v62, 7, v148
	v_bfe_u32 v63, v148, 4, 3
	v_xor_b32_e32 v63, v63, v62
	v_sub_u32_e32 v63, v63, v62
	v_lshlrev_b32_e32 v62, 4, v63
	v_add_u32_e32 v62, 0x280, v62
	v_ashrrev_i32_e32 v63, 31, v62
	v_mfma_f32_16x16x32_f16 v[84:87], v[224:227], v[228:231], v[84:87]
	ds_read_b128 v[224:227], v136 offset:36864
	v_mfma_f32_16x16x32_f16 v[80:83], v[232:235], v[220:223], v[80:83]
	ds_read_b128 v[220:223], v133 offset:4096
	v_mfma_f32_16x16x32_f16 v[88:91], v[232:235], v[228:231], v[88:91]
	ds_read_b128 v[228:231], v133 offset:6144
	s_waitcnt lgkmcnt(4)
	v_mfma_f32_16x16x32_f16 v[138:141], v[202:205], v[198:201], v[138:141]
	ds_read_b128 v[232:235], v136 offset:38912
	s_waitcnt lgkmcnt(4)
	v_mfma_f32_16x16x32_f16 v[92:95], v[202:205], v[206:209], v[92:95]
	v_lshl_add_u64 v[32:33], v[108:109], 0, v[62:63]
	s_mov_b32 m0, s61
	s_nop 0
	global_load_lds_dwordx4 v[32:33], off
	v_mfma_f32_16x16x32_f16 v[142:145], v[210:213], v[198:201], v[142:145]
	v_lshl_add_u64 v[36:37], v[110:111], 0, v[62:63]
	s_mov_b32 m0, s69
	s_nop 0
	global_load_lds_dwordx4 v[36:37], off
	v_mfma_f32_16x16x32_f16 v[158:161], v[210:213], v[206:209], v[158:161]
	v_lshl_add_u64 v[40:41], v[112:113], 0, v[62:63]
	s_mov_b32 m0, s73
	s_nop 0
	global_load_lds_dwordx4 v[40:41], off
	s_waitcnt lgkmcnt(2)
	v_mfma_f32_16x16x32_f16 v[166:169], v[202:205], v[220:223], v[166:169]
	v_lshl_add_u64 v[44:45], v[114:115], 0, v[62:63]
	s_mov_b32 m0, s65
	s_nop 0
	global_load_lds_dwordx4 v[44:45], off
	s_waitcnt lgkmcnt(1)
	v_mfma_f32_16x16x32_f16 v[68:71], v[202:205], v[228:231], v[68:71]
	ds_read_b128 v[202:205], v135 offset:32768
	v_mfma_f32_16x16x32_f16 v[190:193], v[210:213], v[220:223], v[190:193]
	v_lshl_add_u64 v[48:49], v[116:117], 0, v[62:63]
	s_mov_b32 m0, s63
	s_nop 0
	global_load_lds_dwordx4 v[48:49], off
	v_mfma_f32_16x16x32_f16 v[76:79], v[210:213], v[228:231], v[76:79]
	ds_read_b128 v[210:213], v135 offset:34816
	v_mfma_f32_16x16x32_f16 v[154:157], v[224:227], v[198:201], v[154:157]
	v_lshl_add_u64 v[52:53], v[118:119], 0, v[62:63]
	s_mov_b32 m0, s71
	s_nop 0
	global_load_lds_dwordx4 v[52:53], off
	v_mfma_f32_16x16x32_f16 v[162:165], v[224:227], v[206:209], v[162:165]
	v_lshl_add_u64 v[56:57], v[120:121], 0, v[62:63]
	s_mov_b32 m0, s75
	s_nop 0
	global_load_lds_dwordx4 v[56:57], off
	s_waitcnt lgkmcnt(2)
	v_mfma_f32_16x16x32_f16 v[64:67], v[232:235], v[198:201], v[64:67]
	ds_read_b128 v[198:201], v134
	v_mfma_f32_16x16x32_f16 v[72:75], v[232:235], v[206:209], v[72:75]
	ds_read_b128 v[206:209], v134 offset:2048
	v_mfma_f32_16x16x32_f16 v[194:197], v[224:227], v[220:223], v[194:197]
	v_lshl_add_u64 v[60:61], v[122:123], 0, v[62:63]
	s_mov_b32 m0, s67
	s_nop 0
	global_load_lds_dwordx4 v[60:61], off
	v_mfma_f32_16x16x32_f16 v[84:87], v[224:227], v[228:231], v[84:87]
	ds_read_b128 v[224:227], v135 offset:36864
	v_mfma_f32_16x16x32_f16 v[80:83], v[232:235], v[220:223], v[80:83]
	ds_read_b128 v[220:223], v134 offset:4096
	v_mfma_f32_16x16x32_f16 v[88:91], v[232:235], v[228:231], v[88:91]
	ds_read_b128 v[228:231], v134 offset:6144
	ds_read_b128 v[232:235], v135 offset:38912
	s_waitcnt vmcnt(0) lgkmcnt(0)
	s_barrier
	v_mfma_f32_16x16x32_f16 v[138:141], v[202:205], v[198:201], v[138:141]
	v_mfma_f32_16x16x32_f16 v[92:95], v[202:205], v[206:209], v[92:95]
	v_mfma_f32_16x16x32_f16 v[142:145], v[210:213], v[198:201], v[142:145]
	v_mfma_f32_16x16x32_f16 v[158:161], v[210:213], v[206:209], v[158:161]
	v_mfma_f32_16x16x32_f16 v[166:169], v[202:205], v[220:223], v[166:169]
	v_mfma_f32_16x16x32_f16 v[68:71], v[202:205], v[228:231], v[68:71]
	ds_read_b128 v[202:205], v136 offset:49152
	v_mfma_f32_16x16x32_f16 v[190:193], v[210:213], v[220:223], v[190:193]
	v_mfma_f32_16x16x32_f16 v[76:79], v[210:213], v[228:231], v[76:79]
	ds_read_b128 v[210:213], v136 offset:51200
	v_mfma_f32_16x16x32_f16 v[154:157], v[224:227], v[198:201], v[154:157]
	v_mfma_f32_16x16x32_f16 v[162:165], v[224:227], v[206:209], v[162:165]
	v_mfma_f32_16x16x32_f16 v[64:67], v[232:235], v[198:201], v[64:67]
	ds_read_b128 v[198:201], v133 offset:16384
	v_mfma_f32_16x16x32_f16 v[72:75], v[232:235], v[206:209], v[72:75]
	ds_read_b128 v[206:209], v133 offset:18432
	v_mfma_f32_16x16x32_f16 v[194:197], v[224:227], v[220:223], v[194:197]
	v_and_b32_e32 v30, 7, v148
	v_bfe_u32 v31, v148, 4, 3
	v_xor_b32_e32 v31, v31, v30
	v_sub_u32_e32 v31, v31, v30
	v_lshlrev_b32_e32 v30, 4, v31
	v_add_u32_e32 v30, 0x300, v30
	v_ashrrev_i32_e32 v31, 31, v30
	v_mfma_f32_16x16x32_f16 v[84:87], v[224:227], v[228:231], v[84:87]
	ds_read_b128 v[224:227], v136 offset:53248
	v_mfma_f32_16x16x32_f16 v[80:83], v[232:235], v[220:223], v[80:83]
	ds_read_b128 v[220:223], v133 offset:20480
	v_mfma_f32_16x16x32_f16 v[88:91], v[232:235], v[228:231], v[88:91]
	ds_read_b128 v[228:231], v133 offset:22528
	s_waitcnt lgkmcnt(4)
; #define GL_LOAD(s_, kt_) if (VAR != 1) { a##s_##0 = GL_A(0, kt_); a##s_##1 = GL_A(1, kt_); a##s_##2 = GL_A(2, kt_); a##s_##3 = GL_A(3, kt_); b##s_##0 = GL_B(0, kt_); b##s_##1 = GL_B(1, kt_); b##s_##2 = GL_B(2, kt_); b##s_##3 = GL_B(3, kt_); }
; #define LDS_STORE(s_, buf_) if (VAR != 2) { LDS_ST1(sA, 0, buf_, a##s_##0) LDS_ST1(sA, 1, buf_, a##s_##1) LDS_ST1(sA, 2, buf_, a##s_##2) LDS_ST1(sA, 3, buf_, a##s_##3) LDS_ST1(sB, 0, buf_, b##s_##0) LDS_ST1(sB, 1, buf_, b##s_##1) LDS_ST1(sB, 2, buf_, b##s_##2) LDS_ST1(sB, 3, buf_, b##s_##3) }
;     ...
;   GL_LOAD(0, 0)
;   GL_LOAD(1, 1)
;   LDS_STORE(0, 0)
;   if (VAR != 4) __syncthreads();
; #pragma unroll
;   for (int kt = 0; kt < nk; kt += 2) {
;     if (kt + 2 < nk) { GL_LOAD(0, kt + 2) }
;     MMA_TILE(0)
;     LDS_STORE(1, 1)
;     if (VAR != 4) __syncthreads();
;     if (kt + 3 < nk) { GL_LOAD(1, kt + 3) }
;     MMA_TILE(1)
;     if (kt + 2 < nk) { LDS_STORE(0, 0) }
;     if (VAR != 4) __syncthreads();
	v_mfma_f32_16x16x32_f16 v[138:141], v[202:205], v[198:201], v[138:141]
	ds_read_b128 v[232:235], v136 offset:55296
	s_waitcnt lgkmcnt(4)
	v_mfma_f32_16x16x32_f16 v[92:95], v[202:205], v[206:209], v[92:95]
	v_lshl_add_u64 v[0:1], v[108:109], 0, v[30:31]
	s_mov_b32 m0, s60
	s_nop 0
	global_load_lds_dwordx4 v[0:1], off
	v_mfma_f32_16x16x32_f16 v[142:145], v[210:213], v[198:201], v[142:145]
	v_lshl_add_u64 v[4:5], v[110:111], 0, v[30:31]
	s_mov_b32 m0, s68
	s_nop 0
	global_load_lds_dwordx4 v[4:5], off
	v_mfma_f32_16x16x32_f16 v[158:161], v[210:213], v[206:209], v[158:161]
	v_lshl_add_u64 v[8:9], v[112:113], 0, v[30:31]
	s_mov_b32 m0, s72
	s_nop 0
	global_load_lds_dwordx4 v[8:9], off
	s_waitcnt lgkmcnt(2)
	v_mfma_f32_16x16x32_f16 v[166:169], v[202:205], v[220:223], v[166:169]
	v_lshl_add_u64 v[12:13], v[114:115], 0, v[30:31]
	s_mov_b32 m0, s64
	s_nop 0
	global_load_lds_dwordx4 v[12:13], off
	s_waitcnt lgkmcnt(1)
	v_mfma_f32_16x16x32_f16 v[68:71], v[202:205], v[228:231], v[68:71]
	ds_read_b128 v[202:205], v135 offset:49152
	v_mfma_f32_16x16x32_f16 v[190:193], v[210:213], v[220:223], v[190:193]
	v_lshl_add_u64 v[16:17], v[116:117], 0, v[30:31]
	s_mov_b32 m0, s62
	s_nop 0
	global_load_lds_dwordx4 v[16:17], off
	v_mfma_f32_16x16x32_f16 v[76:79], v[210:213], v[228:231], v[76:79]
	ds_read_b128 v[210:213], v135 offset:51200
	v_mfma_f32_16x16x32_f16 v[154:157], v[224:227], v[198:201], v[154:157]
	v_lshl_add_u64 v[20:21], v[118:119], 0, v[30:31]
	s_mov_b32 m0, s70
	s_nop 0
	global_load_lds_dwordx4 v[20:21], off
	v_mfma_f32_16x16x32_f16 v[162:165], v[224:227], v[206:209], v[162:165]
	v_lshl_add_u64 v[24:25], v[120:121], 0, v[30:31]
	s_mov_b32 m0, s74
	s_nop 0
	global_load_lds_dwordx4 v[24:25], off
	s_waitcnt lgkmcnt(2)
	v_mfma_f32_16x16x32_f16 v[64:67], v[232:235], v[198:201], v[64:67]
	ds_read_b128 v[198:201], v134 offset:16384
	v_mfma_f32_16x16x32_f16 v[72:75], v[232:235], v[206:209], v[72:75]
	ds_read_b128 v[206:209], v134 offset:18432
	v_mfma_f32_16x16x32_f16 v[194:197], v[224:227], v[220:223], v[194:197]
	v_lshl_add_u64 v[28:29], v[122:123], 0, v[30:31]
	s_mov_b32 m0, s66
	s_nop 0
	global_load_lds_dwordx4 v[28:29], off
	v_mfma_f32_16x16x32_f16 v[84:87], v[224:227], v[228:231], v[84:87]
	ds_read_b128 v[224:227], v135 offset:53248
	v_mfma_f32_16x16x32_f16 v[80:83], v[232:235], v[220:223], v[80:83]
	ds_read_b128 v[220:223], v134 offset:20480
	v_mfma_f32_16x16x32_f16 v[88:91], v[232:235], v[228:231], v[88:91]
	ds_read_b128 v[228:231], v134 offset:22528
	ds_read_b128 v[232:235], v135 offset:55296
	s_waitcnt vmcnt(0) lgkmcnt(0)
	s_barrier
	v_mfma_f32_16x16x32_f16 v[138:141], v[202:205], v[198:201], v[138:141]
	v_mfma_f32_16x16x32_f16 v[92:95], v[202:205], v[206:209], v[92:95]
	v_mfma_f32_16x16x32_f16 v[142:145], v[210:213], v[198:201], v[142:145]
	v_mfma_f32_16x16x32_f16 v[158:161], v[210:213], v[206:209], v[158:161]
	v_mfma_f32_16x16x32_f16 v[166:169], v[202:205], v[220:223], v[166:169]
	v_mfma_f32_16x16x32_f16 v[68:71], v[202:205], v[228:231], v[68:71]
	ds_read_b128 v[202:205], v136 offset:32768
	v_mfma_f32_16x16x32_f16 v[190:193], v[210:213], v[220:223], v[190:193]
	v_mfma_f32_16x16x32_f16 v[76:79], v[210:213], v[228:231], v[76:79]
	ds_read_b128 v[210:213], v136 offset:34816
	v_mfma_f32_16x16x32_f16 v[154:157], v[224:227], v[198:201], v[154:157]
	v_mfma_f32_16x16x32_f16 v[162:165], v[224:227], v[206:209], v[162:165]
	v_mfma_f32_16x16x32_f16 v[64:67], v[232:235], v[198:201], v[64:67]
	ds_read_b128 v[198:201], v133
	v_mfma_f32_16x16x32_f16 v[72:75], v[232:235], v[206:209], v[72:75]
	ds_read_b128 v[206:209], v133 offset:2048
	v_mfma_f32_16x16x32_f16 v[194:197], v[224:227], v[220:223], v[194:197]
	v_and_b32_e32 v62, 7, v148
	v_bfe_u32 v63, v148, 4, 3
	v_xor_b32_e32 v63, v63, v62
	v_sub_u32_e32 v63, v63, v62
	v_lshlrev_b32_e32 v62, 4, v63
	v_add_u32_e32 v62, 0x380, v62
	v_ashrrev_i32_e32 v63, 31, v62
	v_mfma_f32_16x16x32_f16 v[84:87], v[224:227], v[228:231], v[84:87]
	ds_read_b128 v[224:227], v136 offset:36864
	v_mfma_f32_16x16x32_f16 v[80:83], v[232:235], v[220:223], v[80:83]
	ds_read_b128 v[220:223], v133 offset:4096
	v_mfma_f32_16x16x32_f16 v[88:91], v[232:235], v[228:231], v[88:91]
	ds_read_b128 v[228:231], v133 offset:6144
	s_waitcnt lgkmcnt(4)
	v_mfma_f32_16x16x32_f16 v[138:141], v[202:205], v[198:201], v[138:141]
	ds_read_b128 v[232:235], v136 offset:38912
	s_waitcnt lgkmcnt(4)
	v_mfma_f32_16x16x32_f16 v[92:95], v[202:205], v[206:209], v[92:95]
	v_lshl_add_u64 v[32:33], v[108:109], 0, v[62:63]
	s_mov_b32 m0, s61
	s_nop 0
	global_load_lds_dwordx4 v[32:33], off
	v_mfma_f32_16x16x32_f16 v[142:145], v[210:213], v[198:201], v[142:145]
	v_lshl_add_u64 v[36:37], v[110:111], 0, v[62:63]
	s_mov_b32 m0, s69
	s_nop 0
	global_load_lds_dwordx4 v[36:37], off
	v_mfma_f32_16x16x32_f16 v[158:161], v[210:213], v[206:209], v[158:161]
	v_lshl_add_u64 v[40:41], v[112:113], 0, v[62:63]
	s_mov_b32 m0, s73
	s_nop 0
	global_load_lds_dwordx4 v[40:41], off
	s_waitcnt lgkmcnt(2)
	v_mfma_f32_16x16x32_f16 v[166:169], v[202:205], v[220:223], v[166:169]
	v_lshl_add_u64 v[44:45], v[114:115], 0, v[62:63]
	s_mov_b32 m0, s65
	s_nop 0
	global_load_lds_dwordx4 v[44:45], off
	s_waitcnt lgkmcnt(1)
	v_mfma_f32_16x16x32_f16 v[68:71], v[202:205], v[228:231], v[68:71]
	ds_read_b128 v[202:205], v135 offset:32768
	v_mfma_f32_16x16x32_f16 v[190:193], v[210:213], v[220:223], v[190:193]
	v_lshl_add_u64 v[48:49], v[116:117], 0, v[62:63]
	s_mov_b32 m0, s63
	s_nop 0
	global_load_lds_dwordx4 v[48:49], off
	v_mfma_f32_16x16x32_f16 v[76:79], v[210:213], v[228:231], v[76:79]
	ds_read_b128 v[210:213], v135 offset:34816
	v_mfma_f32_16x16x32_f16 v[154:157], v[224:227], v[198:201], v[154:157]
	v_lshl_add_u64 v[52:53], v[118:119], 0, v[62:63]
	s_mov_b32 m0, s71
	s_nop 0
	global_load_lds_dwordx4 v[52:53], off
	v_mfma_f32_16x16x32_f16 v[162:165], v[224:227], v[206:209], v[162:165]
	v_lshl_add_u64 v[56:57], v[120:121], 0, v[62:63]
	s_mov_b32 m0, s75
	s_nop 0
	global_load_lds_dwordx4 v[56:57], off
	s_waitcnt lgkmcnt(2)
	v_mfma_f32_16x16x32_f16 v[64:67], v[232:235], v[198:201], v[64:67]
	ds_read_b128 v[198:201], v134
	v_mfma_f32_16x16x32_f16 v[72:75], v[232:235], v[206:209], v[72:75]
	ds_read_b128 v[206:209], v134 offset:2048
	v_mfma_f32_16x16x32_f16 v[194:197], v[224:227], v[220:223], v[194:197]
	v_lshl_add_u64 v[60:61], v[122:123], 0, v[62:63]
	s_mov_b32 m0, s67
	s_nop 0
	global_load_lds_dwordx4 v[60:61], off
	v_mfma_f32_16x16x32_f16 v[84:87], v[224:227], v[228:231], v[84:87]
	ds_read_b128 v[224:227], v135 offset:36864
	v_mfma_f32_16x16x32_f16 v[80:83], v[232:235], v[220:223], v[80:83]
	ds_read_b128 v[220:223], v134 offset:4096
	v_mfma_f32_16x16x32_f16 v[88:91], v[232:235], v[228:231], v[88:91]
	ds_read_b128 v[228:231], v134 offset:6144
	ds_read_b128 v[232:235], v135 offset:38912
	s_waitcnt vmcnt(0) lgkmcnt(0)
	s_barrier
; #define GL_LOAD(s_, kt_) if (VAR != 1) { a##s_##0 = GL_A(0, kt_); a##s_##1 = GL_A(1, kt_); a##s_##2 = GL_A(2, kt_); a##s_##3 = GL_A(3, kt_); b##s_##0 = GL_B(0, kt_); b##s_##1 = GL_B(1, kt_); b##s_##2 = GL_B(2, kt_); b##s_##3 = GL_B(3, kt_); }
; #define LDS_STORE(s_, buf_) if (VAR != 2) { LDS_ST1(sA, 0, buf_, a##s_##0) LDS_ST1(sA, 1, buf_, a##s_##1) LDS_ST1(sA, 2, buf_, a##s_##2) LDS_ST1(sA, 3, buf_, a##s_##3) LDS_ST1(sB, 0, buf_, b##s_##0) LDS_ST1(sB, 1, buf_, b##s_##1) LDS_ST1(sB, 2, buf_, b##s_##2) LDS_ST1(sB, 3, buf_, b##s_##3) }
;     ...
;   GL_LOAD(0, 0)
;   GL_LOAD(1, 1)
;   LDS_STORE(0, 0)
;   if (VAR != 4) __syncthreads();
; #pragma unroll
;   for (int kt = 0; kt < nk; kt += 2) {
;     if (kt + 2 < nk) { GL_LOAD(0, kt + 2) }
;     MMA_TILE(0)
;     LDS_STORE(1, 1)
;     if (VAR != 4) __syncthreads();
;     if (kt + 3 < nk) { GL_LOAD(1, kt + 3) }
;     MMA_TILE(1)
;     if (kt + 2 < nk) { LDS_STORE(0, 0) }
;     if (VAR != 4) __syncthreads();
	v_mfma_f32_16x16x32_f16 v[138:141], v[202:205], v[198:201], v[138:141]
	v_mfma_f32_16x16x32_f16 v[92:95], v[202:205], v[206:209], v[92:95]
	v_mfma_f32_16x16x32_f16 v[142:145], v[210:213], v[198:201], v[142:145]
	v_mfma_f32_16x16x32_f16 v[158:161], v[210:213], v[206:209], v[158:161]
	v_mfma_f32_16x16x32_f16 v[166:169], v[202:205], v[220:223], v[166:169]
	v_mfma_f32_16x16x32_f16 v[68:71], v[202:205], v[228:231], v[68:71]
	ds_read_b128 v[202:205], v136 offset:49152
	v_mfma_f32_16x16x32_f16 v[190:193], v[210:213], v[220:223], v[190:193]
	v_mfma_f32_16x16x32_f16 v[76:79], v[210:213], v[228:231], v[76:79]
	ds_read_b128 v[210:213], v136 offset:51200
	v_mfma_f32_16x16x32_f16 v[154:157], v[224:227], v[198:201], v[154:157]
	v_mfma_f32_16x16x32_f16 v[162:165], v[224:227], v[206:209], v[162:165]
	v_mfma_f32_16x16x32_f16 v[64:67], v[232:235], v[198:201], v[64:67]
	ds_read_b128 v[198:201], v133 offset:16384
	v_mfma_f32_16x16x32_f16 v[72:75], v[232:235], v[206:209], v[72:75]
	ds_read_b128 v[206:209], v133 offset:18432
	v_mfma_f32_16x16x32_f16 v[194:197], v[224:227], v[220:223], v[194:197]
	v_and_b32_e32 v30, 7, v148
	v_bfe_u32 v31, v148, 4, 3
	v_xor_b32_e32 v31, v31, v30
	v_sub_u32_e32 v31, v31, v30
	v_lshlrev_b32_e32 v30, 4, v31
	v_add_u32_e32 v30, 0x400, v30
	v_ashrrev_i32_e32 v31, 31, v30
	v_mfma_f32_16x16x32_f16 v[84:87], v[224:227], v[228:231], v[84:87]
	ds_read_b128 v[224:227], v136 offset:53248
	v_mfma_f32_16x16x32_f16 v[80:83], v[232:235], v[220:223], v[80:83]
	ds_read_b128 v[220:223], v133 offset:20480
	v_mfma_f32_16x16x32_f16 v[88:91], v[232:235], v[228:231], v[88:91]
	ds_read_b128 v[228:231], v133 offset:22528
	s_waitcnt lgkmcnt(4)
	v_mfma_f32_16x16x32_f16 v[138:141], v[202:205], v[198:201], v[138:141]
	ds_read_b128 v[232:235], v136 offset:55296
	s_waitcnt lgkmcnt(4)
	v_mfma_f32_16x16x32_f16 v[92:95], v[202:205], v[206:209], v[92:95]
	v_lshl_add_u64 v[0:1], v[108:109], 0, v[30:31]
	s_mov_b32 m0, s60
	s_nop 0
	global_load_lds_dwordx4 v[0:1], off
	v_mfma_f32_16x16x32_f16 v[142:145], v[210:213], v[198:201], v[142:145]
	v_lshl_add_u64 v[4:5], v[110:111], 0, v[30:31]
	s_mov_b32 m0, s68
	s_nop 0
	global_load_lds_dwordx4 v[4:5], off
	v_mfma_f32_16x16x32_f16 v[158:161], v[210:213], v[206:209], v[158:161]
	v_lshl_add_u64 v[8:9], v[112:113], 0, v[30:31]
	s_mov_b32 m0, s72
	s_nop 0
	global_load_lds_dwordx4 v[8:9], off
	s_waitcnt lgkmcnt(2)
	v_mfma_f32_16x16x32_f16 v[166:169], v[202:205], v[220:223], v[166:169]
	v_lshl_add_u64 v[12:13], v[114:115], 0, v[30:31]
	s_mov_b32 m0, s64
	s_nop 0
	global_load_lds_dwordx4 v[12:13], off
	s_waitcnt lgkmcnt(1)
	v_mfma_f32_16x16x32_f16 v[68:71], v[202:205], v[228:231], v[68:71]
	ds_read_b128 v[202:205], v135 offset:49152
	v_mfma_f32_16x16x32_f16 v[190:193], v[210:213], v[220:223], v[190:193]
	v_lshl_add_u64 v[16:17], v[116:117], 0, v[30:31]
	s_mov_b32 m0, s62
	s_nop 0
	global_load_lds_dwordx4 v[16:17], off
	v_mfma_f32_16x16x32_f16 v[76:79], v[210:213], v[228:231], v[76:79]
	ds_read_b128 v[210:213], v135 offset:51200
	v_mfma_f32_16x16x32_f16 v[154:157], v[224:227], v[198:201], v[154:157]
	v_lshl_add_u64 v[20:21], v[118:119], 0, v[30:31]
	s_mov_b32 m0, s70
	s_nop 0
	global_load_lds_dwordx4 v[20:21], off
	v_mfma_f32_16x16x32_f16 v[162:165], v[224:227], v[206:209], v[162:165]
	v_lshl_add_u64 v[24:25], v[120:121], 0, v[30:31]
	s_mov_b32 m0, s74
	s_nop 0
	global_load_lds_dwordx4 v[24:25], off
	s_waitcnt lgkmcnt(2)
	v_mfma_f32_16x16x32_f16 v[64:67], v[232:235], v[198:201], v[64:67]
	ds_read_b128 v[198:201], v134 offset:16384
	v_mfma_f32_16x16x32_f16 v[72:75], v[232:235], v[206:209], v[72:75]
	ds_read_b128 v[206:209], v134 offset:18432
	v_mfma_f32_16x16x32_f16 v[194:197], v[224:227], v[220:223], v[194:197]
	v_lshl_add_u64 v[28:29], v[122:123], 0, v[30:31]
	s_mov_b32 m0, s66
	s_nop 0
	global_load_lds_dwordx4 v[28:29], off
	v_mfma_f32_16x16x32_f16 v[84:87], v[224:227], v[228:231], v[84:87]
	ds_read_b128 v[224:227], v135 offset:53248
	v_mfma_f32_16x16x32_f16 v[80:83], v[232:235], v[220:223], v[80:83]
	ds_read_b128 v[220:223], v134 offset:20480
	v_mfma_f32_16x16x32_f16 v[88:91], v[232:235], v[228:231], v[88:91]
	ds_read_b128 v[228:231], v134 offset:22528
	s_waitcnt lgkmcnt(4)
	v_mfma_f32_16x16x32_f16 v[138:141], v[202:205], v[198:201], v[138:141]
	ds_read_b128 v[232:235], v135 offset:55296
	s_waitcnt vmcnt(0) lgkmcnt(0)
	s_barrier
; #define GL_LOAD(s_, kt_) if (VAR != 1) { a##s_##0 = GL_A(0, kt_); a##s_##1 = GL_A(1, kt_); a##s_##2 = GL_A(2, kt_); a##s_##3 = GL_A(3, kt_); b##s_##0 = GL_B(0, kt_); b##s_##1 = GL_B(1, kt_); b##s_##2 = GL_B(2, kt_); b##s_##3 = GL_B(3, kt_); }
; #define LDS_STORE(s_, buf_) if (VAR != 2) { LDS_ST1(sA, 0, buf_, a##s_##0) LDS_ST1(sA, 1, buf_, a##s_##1) LDS_ST1(sA, 2, buf_, a##s_##2) LDS_ST1(sA, 3, buf_, a##s_##3) LDS_ST1(sB, 0, buf_, b##s_##0) LDS_ST1(sB, 1, buf_, b##s_##1) LDS_ST1(sB, 2, buf_, b##s_##2) LDS_ST1(sB, 3, buf_, b##s_##3) }
;     ...
;   GL_LOAD(0, 0)
;   GL_LOAD(1, 1)
;   LDS_STORE(0, 0)
;   if (VAR != 4) __syncthreads();
; #pragma unroll
;   for (int kt = 0; kt < nk; kt += 2) {
;     if (kt + 2 < nk) { GL_LOAD(0, kt + 2) }
;     MMA_TILE(0)
;     LDS_STORE(1, 1)
;     if (VAR != 4) __syncthreads();
;     if (kt + 3 < nk) { GL_LOAD(1, kt + 3) }
;     MMA_TILE(1)
;     if (kt + 2 < nk) { LDS_STORE(0, 0) }
;     if (VAR != 4) __syncthreads();
	v_mfma_f32_16x16x32_f16 v[142:145], v[210:213], v[198:201], v[142:145]
	ds_read_b128 v[0:3], v133
	v_mfma_f32_16x16x32_f16 v[158:161], v[210:213], v[206:209], v[158:161]
	ds_read_b128 v[4:7], v136 offset:32768
	v_mfma_f32_16x16x32_f16 v[154:157], v[224:227], v[198:201], v[154:157]
	ds_read_b128 v[8:11], v133 offset:2048
	v_mfma_f32_16x16x32_f16 v[162:165], v[224:227], v[206:209], v[162:165]
	ds_read_b128 v[12:15], v136 offset:34816
	v_mfma_f32_16x16x32_f16 v[190:193], v[210:213], v[220:223], v[190:193]
	ds_read_b128 v[16:19], v133 offset:4096
	v_mfma_f32_16x16x32_f16 v[210:213], v[210:213], v[228:231], v[76:79]
	ds_read_b128 v[20:23], v136 offset:36864
	v_mfma_f32_16x16x32_f16 v[194:197], v[224:227], v[220:223], v[194:197]
	ds_read_b128 v[24:27], v133 offset:6144
	v_mfma_f32_16x16x32_f16 v[224:227], v[224:227], v[228:231], v[84:87]
	ds_read_b128 v[28:31], v136 offset:38912
	v_mfma_f32_16x16x32_f16 v[198:201], v[232:235], v[198:201], v[64:67]
	s_nop 2
	v_mfma_f32_16x16x32_f16 v[236:239], v[202:205], v[206:209], v[92:95]
	v_mfma_f32_16x16x32_f16 v[206:209], v[232:235], v[206:209], v[72:75]
	v_mfma_f32_16x16x32_f16 v[166:169], v[202:205], v[220:223], v[166:169]
	v_mfma_f32_16x16x32_f16 v[220:223], v[232:235], v[220:223], v[80:83]
	v_mfma_f32_16x16x32_f16 v[202:205], v[202:205], v[228:231], v[68:71]
	v_mfma_f32_16x16x32_f16 v[228:231], v[232:235], v[228:231], v[88:91]
	ds_read_b128 v[232:235], v135 offset:38912
	s_nop 0
	s_waitcnt lgkmcnt(7)
	v_mfma_f32_16x16x32_f16 v[138:141], v[4:7], v[0:3], v[138:141]
	s_waitcnt lgkmcnt(5)
	v_mfma_f32_16x16x32_f16 v[142:145], v[12:15], v[0:3], v[142:145]
	s_waitcnt lgkmcnt(3)
	v_mfma_f32_16x16x32_f16 v[154:157], v[20:23], v[0:3], v[154:157]
	s_waitcnt lgkmcnt(1)
	v_mfma_f32_16x16x32_f16 v[0:3], v[28:31], v[0:3], v[198:201]
	v_mfma_f32_16x16x32_f16 v[198:201], v[4:7], v[8:11], v[236:239]
	v_mfma_f32_16x16x32_f16 v[158:161], v[12:15], v[8:11], v[158:161]
	v_and_b32_e32 v62, 7, v148
	v_bfe_u32 v63, v148, 4, 3
	v_xor_b32_e32 v63, v63, v62
	v_sub_u32_e32 v63, v63, v62
	v_lshlrev_b32_e32 v62, 4, v63
	v_add_u32_e32 v62, 0x480, v62
	v_ashrrev_i32_e32 v63, 31, v62
	v_lshl_add_u64 v[32:33], v[108:109], 0, v[62:63]
	s_mov_b32 m0, s61
	s_nop 0
	global_load_lds_dwordx4 v[32:33], off
	v_mfma_f32_16x16x32_f16 v[166:169], v[4:7], v[16:19], v[166:169]
	v_lshl_add_u64 v[36:37], v[110:111], 0, v[62:63]
	s_mov_b32 m0, s69
	s_nop 0
	global_load_lds_dwordx4 v[36:37], off
	v_lshl_add_u64 v[40:41], v[112:113], 0, v[62:63]
	s_mov_b32 m0, s73
	s_nop 0
	global_load_lds_dwordx4 v[40:41], off
	v_mfma_f32_16x16x32_f16 v[4:7], v[4:7], v[24:27], v[202:205]
	s_nop 2
	ds_read_b128 v[202:205], v135 offset:32768
	v_lshl_add_u64 v[44:45], v[114:115], 0, v[62:63]
	s_mov_b32 m0, s65
	s_nop 0
	global_load_lds_dwordx4 v[44:45], off
	v_mfma_f32_16x16x32_f16 v[190:193], v[12:15], v[16:19], v[190:193]
	v_lshl_add_u64 v[48:49], v[116:117], 0, v[62:63]
	s_mov_b32 m0, s63
	s_nop 0
	global_load_lds_dwordx4 v[48:49], off
	v_mfma_f32_16x16x32_f16 v[12:15], v[12:15], v[24:27], v[210:213]
	s_nop 2
	ds_read_b128 v[210:213], v135 offset:34816
	v_lshl_add_u64 v[52:53], v[118:119], 0, v[62:63]
	s_mov_b32 m0, s71
	s_nop 0
	global_load_lds_dwordx4 v[52:53], off
	v_mfma_f32_16x16x32_f16 v[162:165], v[20:23], v[8:11], v[162:165]
	v_lshl_add_u64 v[56:57], v[120:121], 0, v[62:63]
	s_mov_b32 m0, s75
	s_nop 0
	global_load_lds_dwordx4 v[56:57], off
	v_lshl_add_u64 v[60:61], v[122:123], 0, v[62:63]
	s_mov_b32 m0, s67
	s_nop 0
	global_load_lds_dwordx4 v[60:61], off
	v_mfma_f32_16x16x32_f16 v[8:11], v[28:31], v[8:11], v[206:209]
	s_nop 2
	ds_read_b128 v[206:209], v134 offset:2048
	v_mfma_f32_16x16x32_f16 v[194:197], v[20:23], v[16:19], v[194:197]
	v_mfma_f32_16x16x32_f16 v[20:23], v[20:23], v[24:27], v[224:227]
	s_nop 2
	ds_read_b128 v[224:227], v135 offset:36864
	v_mfma_f32_16x16x32_f16 v[16:19], v[28:31], v[16:19], v[220:223]
	s_nop 2
	ds_read_b128 v[220:223], v134 offset:4096
	v_mfma_f32_16x16x32_f16 v[24:27], v[28:31], v[24:27], v[228:231]
	ds_read_b128 v[28:31], v134
	s_waitcnt lgkmcnt(0)
	v_mfma_f32_16x16x32_f16 v[138:141], v[202:205], v[28:31], v[138:141]
	ds_read_b128 v[228:231], v134 offset:6144
	s_waitcnt vmcnt(0) lgkmcnt(0)
	s_barrier
	v_mfma_f32_16x16x32_f16 v[142:145], v[210:213], v[28:31], v[142:145]
	ds_read_b128 v[32:35], v133 offset:16384
	v_mfma_f32_16x16x32_f16 v[158:161], v[210:213], v[206:209], v[158:161]
	ds_read_b128 v[36:39], v136 offset:49152
	v_mfma_f32_16x16x32_f16 v[154:157], v[224:227], v[28:31], v[154:157]
	ds_read_b128 v[40:43], v133 offset:18432
	v_mfma_f32_16x16x32_f16 v[162:165], v[224:227], v[206:209], v[162:165]
	ds_read_b128 v[44:47], v136 offset:51200
	v_mfma_f32_16x16x32_f16 v[190:193], v[210:213], v[220:223], v[190:193]
	ds_read_b128 v[48:51], v133 offset:20480
	v_mfma_f32_16x16x32_f16 v[210:213], v[210:213], v[228:231], v[12:15]
	ds_read_b128 v[52:55], v136 offset:53248
	v_mfma_f32_16x16x32_f16 v[194:197], v[224:227], v[220:223], v[194:197]
	ds_read_b128 v[56:59], v133 offset:22528
	v_mfma_f32_16x16x32_f16 v[224:227], v[224:227], v[228:231], v[20:23]
	ds_read_b128 v[60:63], v136 offset:55296
	v_mfma_f32_16x16x32_f16 v[236:239], v[232:235], v[28:31], v[0:3]
	v_mfma_f32_16x16x32_f16 v[198:201], v[202:205], v[206:209], v[198:201]
	v_mfma_f32_16x16x32_f16 v[206:209], v[232:235], v[206:209], v[8:11]
	v_mfma_f32_16x16x32_f16 v[166:169], v[202:205], v[220:223], v[166:169]
	v_mfma_f32_16x16x32_f16 v[220:223], v[232:235], v[220:223], v[16:19]
	v_mfma_f32_16x16x32_f16 v[202:205], v[202:205], v[228:231], v[4:7]
	v_mfma_f32_16x16x32_f16 v[228:231], v[232:235], v[228:231], v[24:27]
	ds_read_b128 v[232:235], v135 offset:55296
	s_nop 1
	s_waitcnt lgkmcnt(7)
; #define GL_LOAD(s_, kt_) if (VAR != 1) { a##s_##0 = GL_A(0, kt_); a##s_##1 = GL_A(1, kt_); a##s_##2 = GL_A(2, kt_); a##s_##3 = GL_A(3, kt_); b##s_##0 = GL_B(0, kt_); b##s_##1 = GL_B(1, kt_); b##s_##2 = GL_B(2, kt_); b##s_##3 = GL_B(3, kt_); }
; #define LDS_STORE(s_, buf_) if (VAR != 2) { LDS_ST1(sA, 0, buf_, a##s_##0) LDS_ST1(sA, 1, buf_, a##s_##1) LDS_ST1(sA, 2, buf_, a##s_##2) LDS_ST1(sA, 3, buf_, a##s_##3) LDS_ST1(sB, 0, buf_, b##s_##0) LDS_ST1(sB, 1, buf_, b##s_##1) LDS_ST1(sB, 2, buf_, b##s_##2) LDS_ST1(sB, 3, buf_, b##s_##3) }
;     ...
;   GL_LOAD(0, 0)
;   GL_LOAD(1, 1)
;   LDS_STORE(0, 0)
;   if (VAR != 4) __syncthreads();
; #pragma unroll
;   for (int kt = 0; kt < nk; kt += 2) {
;     if (kt + 2 < nk) { GL_LOAD(0, kt + 2) }
;     MMA_TILE(0)
;     LDS_STORE(1, 1)
;     if (VAR != 4) __syncthreads();
;     if (kt + 3 < nk) { GL_LOAD(1, kt + 3) }
;     MMA_TILE(1)
;     if (kt + 2 < nk) { LDS_STORE(0, 0) }
;     if (VAR != 4) __syncthreads();
	v_mfma_f32_16x16x32_f16 v[138:141], v[36:39], v[32:35], v[138:141]
	s_waitcnt lgkmcnt(6)
	v_mfma_f32_16x16x32_f16 v[198:201], v[36:39], v[40:43], v[198:201]
	s_waitcnt lgkmcnt(5)
	v_mfma_f32_16x16x32_f16 v[142:145], v[44:47], v[32:35], v[142:145]
	v_mfma_f32_16x16x32_f16 v[158:161], v[44:47], v[40:43], v[158:161]
	s_waitcnt lgkmcnt(4)
	v_mfma_f32_16x16x32_f16 v[166:169], v[36:39], v[48:51], v[166:169]
	v_and_b32_e32 v94, 7, v148
	v_bfe_u32 v95, v148, 4, 3
	v_xor_b32_e32 v95, v95, v94
	v_sub_u32_e32 v95, v95, v94
	v_lshlrev_b32_e32 v94, 4, v95
	v_add_u32_e32 v94, 0x500, v94
	v_ashrrev_i32_e32 v95, 31, v94
	s_waitcnt lgkmcnt(2)
	v_mfma_f32_16x16x32_f16 v[36:39], v[36:39], v[56:59], v[202:205]
	s_nop 2
	ds_read_b128 v[202:205], v135 offset:49152
	v_lshl_add_u64 v[64:65], v[108:109], 0, v[94:95]
	s_mov_b32 m0, s60
	s_nop 0
	global_load_lds_dwordx4 v[64:65], off
	v_mfma_f32_16x16x32_f16 v[190:193], v[44:47], v[48:51], v[190:193]
	v_lshl_add_u64 v[68:69], v[110:111], 0, v[94:95]
	s_mov_b32 m0, s68
	s_nop 0
	global_load_lds_dwordx4 v[68:69], off
	v_lshl_add_u64 v[72:73], v[112:113], 0, v[94:95]
	s_mov_b32 m0, s72
	s_nop 0
	global_load_lds_dwordx4 v[72:73], off
	v_mfma_f32_16x16x32_f16 v[44:47], v[44:47], v[56:59], v[210:213]
	s_nop 2
	ds_read_b128 v[210:213], v135 offset:51200
	v_mfma_f32_16x16x32_f16 v[154:157], v[52:55], v[32:35], v[154:157]
	v_lshl_add_u64 v[76:77], v[114:115], 0, v[94:95]
	s_mov_b32 m0, s64
	s_nop 0
	global_load_lds_dwordx4 v[76:77], off
	v_mfma_f32_16x16x32_f16 v[162:165], v[52:55], v[40:43], v[162:165]
	v_lshl_add_u64 v[80:81], v[116:117], 0, v[94:95]
	s_mov_b32 m0, s62
	s_nop 0
	global_load_lds_dwordx4 v[80:81], off
	s_waitcnt lgkmcnt(3)
	v_mfma_f32_16x16x32_f16 v[32:35], v[60:63], v[32:35], v[236:239]
	v_lshl_add_u64 v[84:85], v[118:119], 0, v[94:95]
	s_mov_b32 m0, s70
	s_nop 0
	global_load_lds_dwordx4 v[84:85], off
	v_mfma_f32_16x16x32_f16 v[40:43], v[60:63], v[40:43], v[206:209]
	s_nop 2
	ds_read_b128 v[206:209], v134 offset:18432
	v_mfma_f32_16x16x32_f16 v[194:197], v[52:55], v[48:51], v[194:197]
	v_lshl_add_u64 v[88:89], v[120:121], 0, v[94:95]
	s_mov_b32 m0, s74
	s_nop 0
	global_load_lds_dwordx4 v[88:89], off
	v_mfma_f32_16x16x32_f16 v[52:55], v[52:55], v[56:59], v[224:227]
	s_nop 2
	ds_read_b128 v[224:227], v135 offset:53248
	v_mfma_f32_16x16x32_f16 v[48:51], v[60:63], v[48:51], v[220:223]
	s_nop 2
	ds_read_b128 v[220:223], v134 offset:20480
	v_mfma_f32_16x16x32_f16 v[56:59], v[60:63], v[56:59], v[228:231]
	ds_read_b128 v[60:63], v134 offset:16384
	s_waitcnt lgkmcnt(0)
	v_mfma_f32_16x16x32_f16 v[138:141], v[202:205], v[60:63], v[138:141]
	ds_read_b128 v[228:231], v134 offset:22528
	v_lshl_add_u64 v[92:93], v[122:123], 0, v[94:95]
	s_mov_b32 m0, s66
	s_nop 0
	global_load_lds_dwordx4 v[92:93], off
	s_waitcnt vmcnt(0) lgkmcnt(0)
	s_barrier
	v_mfma_f32_16x16x32_f16 v[142:145], v[210:213], v[60:63], v[142:145]
	ds_read_b128 v[64:67], v133
	v_mfma_f32_16x16x32_f16 v[158:161], v[210:213], v[206:209], v[158:161]
	ds_read_b128 v[68:71], v136 offset:32768
	v_mfma_f32_16x16x32_f16 v[154:157], v[224:227], v[60:63], v[154:157]
	ds_read_b128 v[72:75], v133 offset:2048
	v_mfma_f32_16x16x32_f16 v[162:165], v[224:227], v[206:209], v[162:165]
	ds_read_b128 v[76:79], v136 offset:34816
	v_mfma_f32_16x16x32_f16 v[190:193], v[210:213], v[220:223], v[190:193]
	ds_read_b128 v[80:83], v133 offset:4096
	v_mfma_f32_16x16x32_f16 v[210:213], v[210:213], v[228:231], v[44:47]
	ds_read_b128 v[84:87], v136 offset:36864
	v_mfma_f32_16x16x32_f16 v[194:197], v[224:227], v[220:223], v[194:197]
	ds_read_b128 v[88:91], v133 offset:6144
	v_mfma_f32_16x16x32_f16 v[224:227], v[224:227], v[228:231], v[52:55]
	ds_read_b128 v[92:95], v136 offset:38912
	v_mfma_f32_16x16x32_f16 v[236:239], v[232:235], v[60:63], v[32:35]
	s_nop 0
	v_mfma_f32_16x16x32_f16 v[198:201], v[202:205], v[206:209], v[198:201]
	v_mfma_f32_16x16x32_f16 v[206:209], v[232:235], v[206:209], v[40:43]
	v_mfma_f32_16x16x32_f16 v[166:169], v[202:205], v[220:223], v[166:169]
	v_mfma_f32_16x16x32_f16 v[220:223], v[232:235], v[220:223], v[48:51]
	v_mfma_f32_16x16x32_f16 v[202:205], v[202:205], v[228:231], v[36:39]
	v_mfma_f32_16x16x32_f16 v[228:231], v[232:235], v[228:231], v[56:59]
	ds_read_b128 v[232:235], v135 offset:38912
	s_nop 1
	s_waitcnt lgkmcnt(7)
	v_mfma_f32_16x16x32_f16 v[138:141], v[68:71], v[64:67], v[138:141]
	s_waitcnt lgkmcnt(6)
	v_mfma_f32_16x16x32_f16 v[198:201], v[68:71], v[72:75], v[198:201]
	s_waitcnt lgkmcnt(5)
	v_mfma_f32_16x16x32_f16 v[142:145], v[76:79], v[64:67], v[142:145]
	v_mfma_f32_16x16x32_f16 v[158:161], v[76:79], v[72:75], v[158:161]
	s_waitcnt lgkmcnt(4)
	v_mfma_f32_16x16x32_f16 v[166:169], v[68:71], v[80:83], v[166:169]
	v_and_b32_e32 v10, 7, v148
	v_bfe_u32 v11, v148, 4, 3
	v_xor_b32_e32 v11, v11, v10
	v_sub_u32_e32 v11, v11, v10
	v_lshlrev_b32_e32 v10, 4, v11
	v_add_u32_e32 v10, 0x580, v10
	v_ashrrev_i32_e32 v11, 31, v10
	v_lshl_add_u64 v[28:29], v[108:109], 0, v[10:11]
	s_mov_b32 m0, s61
	s_nop 0
	global_load_lds_dwordx4 v[28:29], off
	s_waitcnt lgkmcnt(2)
	v_mfma_f32_16x16x32_f16 v[68:71], v[68:71], v[88:91], v[202:205]
	s_nop 2
	ds_read_b128 v[202:205], v135 offset:32768
	v_lshl_add_u64 v[24:25], v[110:111], 0, v[10:11]
	s_mov_b32 m0, s69
	s_nop 0
	global_load_lds_dwordx4 v[24:25], off
	v_mfma_f32_16x16x32_f16 v[190:193], v[76:79], v[80:83], v[190:193]
	v_lshl_add_u64 v[12:13], v[112:113], 0, v[10:11]
	s_mov_b32 m0, s73
	s_nop 0
	global_load_lds_dwordx4 v[12:13], off
	v_lshl_add_u64 v[16:17], v[114:115], 0, v[10:11]
	s_mov_b32 m0, s65
	s_nop 0
	global_load_lds_dwordx4 v[16:17], off
	v_mfma_f32_16x16x32_f16 v[76:79], v[76:79], v[88:91], v[210:213]
	s_nop 2
	ds_read_b128 v[210:213], v135 offset:34816
	v_mfma_f32_16x16x32_f16 v[154:157], v[84:87], v[64:67], v[154:157]
	v_lshl_add_u64 v[20:21], v[116:117], 0, v[10:11]
	s_mov_b32 m0, s63
	s_nop 0
	global_load_lds_dwordx4 v[20:21], off
	v_mfma_f32_16x16x32_f16 v[162:165], v[84:87], v[72:75], v[162:165]
	v_lshl_add_u64 v[0:1], v[118:119], 0, v[10:11]
	s_mov_b32 m0, s71
	s_nop 0
	global_load_lds_dwordx4 v[0:1], off
	s_waitcnt lgkmcnt(3)
	v_mfma_f32_16x16x32_f16 v[64:67], v[92:95], v[64:67], v[236:239]
	v_lshl_add_u64 v[4:5], v[120:121], 0, v[10:11]
	s_mov_b32 m0, s75
	s_nop 0
	global_load_lds_dwordx4 v[4:5], off
	v_mfma_f32_16x16x32_f16 v[72:75], v[92:95], v[72:75], v[206:209]
	s_nop 2
	ds_read_b128 v[206:209], v134 offset:2048
	v_mfma_f32_16x16x32_f16 v[194:197], v[84:87], v[80:83], v[194:197]
	v_lshl_add_u64 v[8:9], v[122:123], 0, v[10:11]
	s_mov_b32 m0, s67
	s_nop 0
	global_load_lds_dwordx4 v[8:9], off
	v_mfma_f32_16x16x32_f16 v[84:87], v[84:87], v[88:91], v[224:227]
	s_nop 2
	ds_read_b128 v[224:227], v135 offset:36864
	v_mfma_f32_16x16x32_f16 v[80:83], v[92:95], v[80:83], v[220:223]
	s_nop 2
	ds_read_b128 v[220:223], v134 offset:4096
	v_mfma_f32_16x16x32_f16 v[88:91], v[92:95], v[88:91], v[228:231]
	ds_read_b128 v[92:95], v134
	s_nop 1
	ds_read_b128 v[228:231], v134 offset:6144
	s_waitcnt vmcnt(0) lgkmcnt(0)
	s_barrier
; #define GL_LOAD(s_, kt_) if (VAR != 1) { a##s_##0 = GL_A(0, kt_); a##s_##1 = GL_A(1, kt_); a##s_##2 = GL_A(2, kt_); a##s_##3 = GL_A(3, kt_); b##s_##0 = GL_B(0, kt_); b##s_##1 = GL_B(1, kt_); b##s_##2 = GL_B(2, kt_); b##s_##3 = GL_B(3, kt_); }
; #define LDS_STORE(s_, buf_) if (VAR != 2) { LDS_ST1(sA, 0, buf_, a##s_##0) LDS_ST1(sA, 1, buf_, a##s_##1) LDS_ST1(sA, 2, buf_, a##s_##2) LDS_ST1(sA, 3, buf_, a##s_##3) LDS_ST1(sB, 0, buf_, b##s_##0) LDS_ST1(sB, 1, buf_, b##s_##1) LDS_ST1(sB, 2, buf_, b##s_##2) LDS_ST1(sB, 3, buf_, b##s_##3) }
;     ...
;   GL_LOAD(0, 0)
;   GL_LOAD(1, 1)
;   LDS_STORE(0, 0)
;   if (VAR != 4) __syncthreads();
; #pragma unroll
;   for (int kt = 0; kt < nk; kt += 2) {
;     if (kt + 2 < nk) { GL_LOAD(0, kt + 2) }
;     MMA_TILE(0)
;     LDS_STORE(1, 1)
;     if (VAR != 4) __syncthreads();
;     if (kt + 3 < nk) { GL_LOAD(1, kt + 3) }
;     MMA_TILE(1)
;     if (kt + 2 < nk) { LDS_STORE(0, 0) }
;     if (VAR != 4) __syncthreads();
	v_mfma_f32_16x16x32_f16 v[138:141], v[202:205], v[92:95], v[138:141]
	v_mfma_f32_16x16x32_f16 v[142:145], v[210:213], v[92:95], v[142:145]
	v_mfma_f32_16x16x32_f16 v[154:157], v[224:227], v[92:95], v[154:157]
	v_mfma_f32_16x16x32_f16 v[64:67], v[232:235], v[92:95], v[64:67]
	v_mfma_f32_16x16x32_f16 v[92:95], v[202:205], v[206:209], v[198:201]
	s_nop 2
	ds_read_b128 v[198:201], v133 offset:16384
	v_mfma_f32_16x16x32_f16 v[158:161], v[210:213], v[206:209], v[158:161]
	v_mfma_f32_16x16x32_f16 v[166:169], v[202:205], v[220:223], v[166:169]
	v_mfma_f32_16x16x32_f16 v[68:71], v[202:205], v[228:231], v[68:71]
	ds_read_b128 v[202:205], v136 offset:49152
	v_mfma_f32_16x16x32_f16 v[190:193], v[210:213], v[220:223], v[190:193]
	v_mfma_f32_16x16x32_f16 v[76:79], v[210:213], v[228:231], v[76:79]
	ds_read_b128 v[210:213], v136 offset:51200
	v_mfma_f32_16x16x32_f16 v[162:165], v[224:227], v[206:209], v[162:165]
	v_mfma_f32_16x16x32_f16 v[72:75], v[232:235], v[206:209], v[72:75]
	ds_read_b128 v[206:209], v133 offset:18432
	v_mfma_f32_16x16x32_f16 v[194:197], v[224:227], v[220:223], v[194:197]
	v_and_b32_e32 v38, 7, v148
	v_bfe_u32 v39, v148, 4, 3
	v_xor_b32_e32 v39, v39, v38
	v_sub_u32_e32 v39, v39, v38
	v_lshlrev_b32_e32 v38, 4, v39
	v_add_u32_e32 v38, 0x600, v38
	v_ashrrev_i32_e32 v39, 31, v38
	v_mfma_f32_16x16x32_f16 v[84:87], v[224:227], v[228:231], v[84:87]
	ds_read_b128 v[224:227], v136 offset:53248
	v_mfma_f32_16x16x32_f16 v[80:83], v[232:235], v[220:223], v[80:83]
	ds_read_b128 v[220:223], v133 offset:20480
	v_mfma_f32_16x16x32_f16 v[88:91], v[232:235], v[228:231], v[88:91]
	ds_read_b128 v[228:231], v133 offset:22528
	s_waitcnt lgkmcnt(5)
	v_mfma_f32_16x16x32_f16 v[138:141], v[202:205], v[198:201], v[138:141]
	ds_read_b128 v[232:235], v136 offset:55296
	s_waitcnt lgkmcnt(4)
	v_mfma_f32_16x16x32_f16 v[92:95], v[202:205], v[206:209], v[92:95]
	v_lshl_add_u64 v[52:53], v[108:109], 0, v[38:39]
	s_mov_b32 m0, s60
	s_nop 0
	global_load_lds_dwordx4 v[52:53], off
	v_mfma_f32_16x16x32_f16 v[142:145], v[210:213], v[198:201], v[142:145]
	v_lshl_add_u64 v[56:57], v[110:111], 0, v[38:39]
	s_mov_b32 m0, s68
	s_nop 0
	global_load_lds_dwordx4 v[56:57], off
	v_mfma_f32_16x16x32_f16 v[158:161], v[210:213], v[206:209], v[158:161]
	v_lshl_add_u64 v[60:61], v[112:113], 0, v[38:39]
	s_mov_b32 m0, s72
	s_nop 0
	global_load_lds_dwordx4 v[60:61], off
	s_waitcnt lgkmcnt(2)
	v_mfma_f32_16x16x32_f16 v[166:169], v[202:205], v[220:223], v[166:169]
	v_lshl_add_u64 v[40:41], v[114:115], 0, v[38:39]
	s_mov_b32 m0, s64
	s_nop 0
	global_load_lds_dwordx4 v[40:41], off
	s_waitcnt lgkmcnt(1)
	v_mfma_f32_16x16x32_f16 v[68:71], v[202:205], v[228:231], v[68:71]
	ds_read_b128 v[202:205], v135 offset:49152
	v_mfma_f32_16x16x32_f16 v[190:193], v[210:213], v[220:223], v[190:193]
	v_lshl_add_u64 v[44:45], v[116:117], 0, v[38:39]
	s_mov_b32 m0, s62
	s_nop 0
	global_load_lds_dwordx4 v[44:45], off
	v_mfma_f32_16x16x32_f16 v[76:79], v[210:213], v[228:231], v[76:79]
	ds_read_b128 v[210:213], v135 offset:51200
	v_mfma_f32_16x16x32_f16 v[154:157], v[224:227], v[198:201], v[154:157]
	v_lshl_add_u64 v[48:49], v[118:119], 0, v[38:39]
	s_mov_b32 m0, s70
	s_nop 0
	global_load_lds_dwordx4 v[48:49], off
	v_mfma_f32_16x16x32_f16 v[162:165], v[224:227], v[206:209], v[162:165]
	v_lshl_add_u64 v[32:33], v[120:121], 0, v[38:39]
	s_mov_b32 m0, s74
	s_nop 0
	global_load_lds_dwordx4 v[32:33], off
	s_waitcnt lgkmcnt(2)
	v_mfma_f32_16x16x32_f16 v[64:67], v[232:235], v[198:201], v[64:67]
	ds_read_b128 v[198:201], v134 offset:16384
	v_mfma_f32_16x16x32_f16 v[72:75], v[232:235], v[206:209], v[72:75]
	ds_read_b128 v[206:209], v134 offset:18432
	v_mfma_f32_16x16x32_f16 v[194:197], v[224:227], v[220:223], v[194:197]
	v_lshl_add_u64 v[36:37], v[122:123], 0, v[38:39]
	s_mov_b32 m0, s66
	s_nop 0
	global_load_lds_dwordx4 v[36:37], off
	v_mfma_f32_16x16x32_f16 v[84:87], v[224:227], v[228:231], v[84:87]
	ds_read_b128 v[224:227], v135 offset:53248
	v_mfma_f32_16x16x32_f16 v[80:83], v[232:235], v[220:223], v[80:83]
	ds_read_b128 v[220:223], v134 offset:20480
	v_mfma_f32_16x16x32_f16 v[88:91], v[232:235], v[228:231], v[88:91]
	ds_read_b128 v[228:231], v134 offset:22528
	ds_read_b128 v[232:235], v135 offset:55296
	s_waitcnt vmcnt(0) lgkmcnt(0)
	s_barrier
; #define GL_LOAD(s_, kt_) if (VAR != 1) { a##s_##0 = GL_A(0, kt_); a##s_##1 = GL_A(1, kt_); a##s_##2 = GL_A(2, kt_); a##s_##3 = GL_A(3, kt_); b##s_##0 = GL_B(0, kt_); b##s_##1 = GL_B(1, kt_); b##s_##2 = GL_B(2, kt_); b##s_##3 = GL_B(3, kt_); }
; #define LDS_STORE(s_, buf_) if (VAR != 2) { LDS_ST1(sA, 0, buf_, a##s_##0) LDS_ST1(sA, 1, buf_, a##s_##1) LDS_ST1(sA, 2, buf_, a##s_##2) LDS_ST1(sA, 3, buf_, a##s_##3) LDS_ST1(sB, 0, buf_, b##s_##0) LDS_ST1(sB, 1, buf_, b##s_##1) LDS_ST1(sB, 2, buf_, b##s_##2) LDS_ST1(sB, 3, buf_, b##s_##3) }
;     ...
;   GL_LOAD(0, 0)
;   GL_LOAD(1, 1)
;   LDS_STORE(0, 0)
;   if (VAR != 4) __syncthreads();
; #pragma unroll
;   for (int kt = 0; kt < nk; kt += 2) {
;     if (kt + 2 < nk) { GL_LOAD(0, kt + 2) }
;     MMA_TILE(0)
;     LDS_STORE(1, 1)
;     if (VAR != 4) __syncthreads();
;     if (kt + 3 < nk) { GL_LOAD(1, kt + 3) }
;     MMA_TILE(1)
;     if (kt + 2 < nk) { LDS_STORE(0, 0) }
;     if (VAR != 4) __syncthreads();
	v_mfma_f32_16x16x32_f16 v[138:141], v[202:205], v[198:201], v[138:141]
	v_and_b32_e32 v6, 7, v148
	v_bfe_u32 v7, v148, 4, 3
	v_xor_b32_e32 v7, v7, v6
	v_sub_u32_e32 v7, v7, v6
	v_lshlrev_b32_e32 v6, 4, v7
	v_add_u32_e32 v6, 0x680, v6
	v_ashrrev_i32_e32 v7, 31, v6
	v_mfma_f32_16x16x32_f16 v[92:95], v[202:205], v[206:209], v[92:95]
	global_load_dwordx4 v[60:63], v[108:109], off offset:1792
	v_mfma_f32_16x16x32_f16 v[142:145], v[210:213], v[198:201], v[142:145]
	global_load_dwordx4 v[48:51], v[110:111], off offset:1792
	v_mfma_f32_16x16x32_f16 v[158:161], v[210:213], v[206:209], v[158:161]
	global_load_dwordx4 v[52:55], v[112:113], off offset:1792
	v_mfma_f32_16x16x32_f16 v[166:169], v[202:205], v[220:223], v[166:169]
	global_load_dwordx4 v[56:59], v[114:115], off offset:1792
	v_mfma_f32_16x16x32_f16 v[68:71], v[202:205], v[228:231], v[68:71]
	ds_read_b128 v[202:205], v136 offset:32768
	v_mfma_f32_16x16x32_f16 v[190:193], v[210:213], v[220:223], v[190:193]
	global_load_dwordx4 v[36:39], v[116:117], off offset:1792
	v_mfma_f32_16x16x32_f16 v[76:79], v[210:213], v[228:231], v[76:79]
	ds_read_b128 v[210:213], v136 offset:34816
	v_mfma_f32_16x16x32_f16 v[154:157], v[224:227], v[198:201], v[154:157]
	global_load_dwordx4 v[40:43], v[118:119], off offset:1792
	v_mfma_f32_16x16x32_f16 v[162:165], v[224:227], v[206:209], v[162:165]
	global_load_dwordx4 v[44:47], v[120:121], off offset:1792
	v_mfma_f32_16x16x32_f16 v[64:67], v[232:235], v[198:201], v[64:67]
	ds_read_b128 v[198:201], v133
	v_mfma_f32_16x16x32_f16 v[72:75], v[232:235], v[206:209], v[72:75]
	ds_read_b128 v[206:209], v133 offset:2048
	v_mfma_f32_16x16x32_f16 v[194:197], v[224:227], v[220:223], v[194:197]
	global_load_dwordx4 v[32:35], v[122:123], off offset:1792
	v_mfma_f32_16x16x32_f16 v[84:87], v[224:227], v[228:231], v[84:87]
	ds_read_b128 v[224:227], v136 offset:36864
	v_mfma_f32_16x16x32_f16 v[80:83], v[232:235], v[220:223], v[80:83]
	ds_read_b128 v[220:223], v133 offset:4096
	v_mfma_f32_16x16x32_f16 v[88:91], v[232:235], v[228:231], v[88:91]
	ds_read_b128 v[228:231], v133 offset:6144
	s_waitcnt lgkmcnt(4)
	v_mfma_f32_16x16x32_f16 v[138:141], v[202:205], v[198:201], v[138:141]
	ds_read_b128 v[232:235], v136 offset:38912
	s_waitcnt lgkmcnt(4)
	v_mfma_f32_16x16x32_f16 v[92:95], v[202:205], v[206:209], v[92:95]
	v_lshl_add_u64 v[20:21], v[108:109], 0, v[6:7]
	s_mov_b32 m0, s61
	s_nop 0
	global_load_lds_dwordx4 v[20:21], off
	v_mfma_f32_16x16x32_f16 v[142:145], v[210:213], v[198:201], v[142:145]
	v_lshl_add_u64 v[24:25], v[110:111], 0, v[6:7]
	s_mov_b32 m0, s69
	s_nop 0
	global_load_lds_dwordx4 v[24:25], off
	v_mfma_f32_16x16x32_f16 v[158:161], v[210:213], v[206:209], v[158:161]
	v_lshl_add_u64 v[28:29], v[112:113], 0, v[6:7]
	s_mov_b32 m0, s73
	s_nop 0
	global_load_lds_dwordx4 v[28:29], off
	s_waitcnt lgkmcnt(2)
	v_mfma_f32_16x16x32_f16 v[166:169], v[202:205], v[220:223], v[166:169]
	v_lshl_add_u64 v[8:9], v[114:115], 0, v[6:7]
	s_mov_b32 m0, s65
	s_nop 0
	global_load_lds_dwordx4 v[8:9], off
	s_waitcnt lgkmcnt(1)
	v_mfma_f32_16x16x32_f16 v[68:71], v[202:205], v[228:231], v[68:71]
	ds_read_b128 v[202:205], v135 offset:32768
	v_mfma_f32_16x16x32_f16 v[190:193], v[210:213], v[220:223], v[190:193]
	v_lshl_add_u64 v[12:13], v[116:117], 0, v[6:7]
	s_mov_b32 m0, s63
	s_nop 0
	global_load_lds_dwordx4 v[12:13], off
	v_mfma_f32_16x16x32_f16 v[76:79], v[210:213], v[228:231], v[76:79]
	ds_read_b128 v[210:213], v135 offset:34816
	v_mfma_f32_16x16x32_f16 v[154:157], v[224:227], v[198:201], v[154:157]
	v_lshl_add_u64 v[16:17], v[118:119], 0, v[6:7]
	s_mov_b32 m0, s71
	s_nop 0
	global_load_lds_dwordx4 v[16:17], off
	v_mfma_f32_16x16x32_f16 v[162:165], v[224:227], v[206:209], v[162:165]
	v_lshl_add_u64 v[0:1], v[120:121], 0, v[6:7]
	s_mov_b32 m0, s75
	s_nop 0
	global_load_lds_dwordx4 v[0:1], off
	s_waitcnt lgkmcnt(2)
	v_mfma_f32_16x16x32_f16 v[64:67], v[232:235], v[198:201], v[64:67]
	ds_read_b128 v[198:201], v134
	v_mfma_f32_16x16x32_f16 v[72:75], v[232:235], v[206:209], v[72:75]
	ds_read_b128 v[206:209], v134 offset:2048
	v_mfma_f32_16x16x32_f16 v[194:197], v[224:227], v[220:223], v[194:197]
	v_lshl_add_u64 v[4:5], v[122:123], 0, v[6:7]
	s_mov_b32 m0, s67
	s_nop 0
	global_load_lds_dwordx4 v[4:5], off
	v_mfma_f32_16x16x32_f16 v[84:87], v[224:227], v[228:231], v[84:87]
	ds_read_b128 v[224:227], v135 offset:36864
	v_mfma_f32_16x16x32_f16 v[80:83], v[232:235], v[220:223], v[80:83]
	ds_read_b128 v[220:223], v134 offset:4096
	v_mfma_f32_16x16x32_f16 v[88:91], v[232:235], v[228:231], v[88:91]
	ds_read_b128 v[228:231], v134 offset:6144
	ds_read_b128 v[232:235], v135 offset:38912
	s_waitcnt vmcnt(0) lgkmcnt(0)
	s_barrier
; #define GL_LOAD(s_, kt_) if (VAR != 1) { a##s_##0 = GL_A(0, kt_); a##s_##1 = GL_A(1, kt_); a##s_##2 = GL_A(2, kt_); a##s_##3 = GL_A(3, kt_); b##s_##0 = GL_B(0, kt_); b##s_##1 = GL_B(1, kt_); b##s_##2 = GL_B(2, kt_); b##s_##3 = GL_B(3, kt_); }
; #define LDS_STORE(s_, buf_) if (VAR != 2) { LDS_ST1(sA, 0, buf_, a##s_##0) LDS_ST1(sA, 1, buf_, a##s_##1) LDS_ST1(sA, 2, buf_, a##s_##2) LDS_ST1(sA, 3, buf_, a##s_##3) LDS_ST1(sB, 0, buf_, b##s_##0) LDS_ST1(sB, 1, buf_, b##s_##1) LDS_ST1(sB, 2, buf_, b##s_##2) LDS_ST1(sB, 3, buf_, b##s_##3) }
;     ...
;   GL_LOAD(0, 0)
;   GL_LOAD(1, 1)
;   LDS_STORE(0, 0)
;   if (VAR != 4) __syncthreads();
; #pragma unroll
;   for (int kt = 0; kt < nk; kt += 2) {
;     if (kt + 2 < nk) { GL_LOAD(0, kt + 2) }
;     MMA_TILE(0)
;     LDS_STORE(1, 1)
;     if (VAR != 4) __syncthreads();
;     if (kt + 3 < nk) { GL_LOAD(1, kt + 3) }
;     MMA_TILE(1)
;     if (kt + 2 < nk) { LDS_STORE(0, 0) }
;     if (VAR != 4) __syncthreads();
	v_mfma_f32_16x16x32_f16 v[138:141], v[202:205], v[198:201], v[138:141]
	global_load_dwordx4 v[28:31], v[108:109], off offset:1920
	v_mfma_f32_16x16x32_f16 v[92:95], v[202:205], v[206:209], v[92:95]
	global_load_dwordx4 v[16:19], v[110:111], off offset:1920
	v_mfma_f32_16x16x32_f16 v[142:145], v[210:213], v[198:201], v[142:145]
	ds_read_b128 v[108:111], v133 offset:16384
	v_mfma_f32_16x16x32_f16 v[158:161], v[210:213], v[206:209], v[158:161]
	global_load_dwordx4 v[20:23], v[112:113], off offset:1920
	v_mfma_f32_16x16x32_f16 v[166:169], v[202:205], v[220:223], v[166:169]
	global_load_dwordx4 v[24:27], v[114:115], off offset:1920
	v_mfma_f32_16x16x32_f16 v[68:71], v[202:205], v[228:231], v[68:71]
	ds_read_b128 v[112:115], v136 offset:49152
	v_mfma_f32_16x16x32_f16 v[190:193], v[210:213], v[220:223], v[190:193]
	ds_read_b128 v[202:205], v136 offset:53248
	v_mfma_f32_16x16x32_f16 v[76:79], v[210:213], v[228:231], v[76:79]
	ds_read_b128 v[210:213], v136 offset:55296
	v_mfma_f32_16x16x32_f16 v[154:157], v[224:227], v[198:201], v[154:157]
	global_load_dwordx4 v[4:7], v[116:117], off offset:1920
	v_mfma_f32_16x16x32_f16 v[162:165], v[224:227], v[206:209], v[162:165]
	global_load_dwordx4 v[8:11], v[118:119], off offset:1920
	v_mfma_f32_16x16x32_f16 v[64:67], v[232:235], v[198:201], v[64:67]
	ds_read_b128 v[116:119], v133 offset:18432
	v_mfma_f32_16x16x32_f16 v[72:75], v[232:235], v[206:209], v[72:75]
	ds_read_b128 v[198:201], v133 offset:20480
	v_mfma_f32_16x16x32_f16 v[194:197], v[224:227], v[220:223], v[194:197]
	ds_read_b128 v[206:209], v133 offset:22528
	v_mfma_f32_16x16x32_f16 v[84:87], v[224:227], v[228:231], v[84:87]
	global_load_dwordx4 v[12:15], v[120:121], off offset:1920
	v_mfma_f32_16x16x32_f16 v[80:83], v[232:235], v[220:223], v[80:83]
	global_load_dwordx4 v[0:3], v[122:123], off offset:1920
	v_mfma_f32_16x16x32_f16 v[88:91], v[232:235], v[228:231], v[88:91]
	ds_read_b128 v[120:123], v136 offset:51200
	s_waitcnt lgkmcnt(6)
	v_mfma_f32_16x16x32_f16 v[138:141], v[112:115], v[108:111], v[138:141]
	ds_write_b128 v101, v[60:63]
	s_waitcnt lgkmcnt(4)
	v_mfma_f32_16x16x32_f16 v[92:95], v[112:115], v[116:119], v[92:95]
	ds_write_b128 v131, v[48:51]
	s_waitcnt lgkmcnt(2)
	v_mfma_f32_16x16x32_f16 v[142:145], v[120:123], v[108:111], v[142:145]
	ds_write_b128 v132, v[52:55]
	v_mfma_f32_16x16x32_f16 v[154:157], v[202:205], v[108:111], v[154:157]
	v_mfma_f32_16x16x32_f16 v[64:67], v[210:213], v[108:111], v[64:67]
	v_mfma_f32_16x16x32_f16 v[108:111], v[120:123], v[116:119], v[158:161]
	ds_write_b128 v130, v[56:59]
	v_mfma_f32_16x16x32_f16 v[158:161], v[202:205], v[116:119], v[162:165]
	v_mfma_f32_16x16x32_f16 v[72:75], v[210:213], v[116:119], v[72:75]
	v_mfma_f32_16x16x32_f16 v[116:119], v[112:115], v[198:201], v[166:169]
	ds_write_b128 v101, v[36:39] offset:32768
	ds_write_b128 v131, v[40:43] offset:32768
	v_mfma_f32_16x16x32_f16 v[68:71], v[112:115], v[206:209], v[68:71]
	ds_read_b128 v[112:115], v134 offset:16384
	ds_write_b128 v132, v[44:47] offset:32768
	v_mfma_f32_16x16x32_f16 v[162:165], v[120:123], v[198:201], v[190:193]
	s_nop 2
	ds_read_b128 v[190:193], v134 offset:18432
	v_mfma_f32_16x16x32_f16 v[76:79], v[120:123], v[206:209], v[76:79]
	ds_read_b128 v[120:123], v135 offset:49152
	ds_write_b128 v130, v[32:35] offset:32768
	v_mfma_f32_16x16x32_f16 v[166:169], v[202:205], v[198:201], v[194:197]
	s_nop 2
	ds_read_b128 v[194:197], v135 offset:51200
	v_mfma_f32_16x16x32_f16 v[84:87], v[202:205], v[206:209], v[84:87]
	ds_read_b128 v[202:205], v135 offset:53248
	v_mfma_f32_16x16x32_f16 v[80:83], v[210:213], v[198:201], v[80:83]
	ds_read_b128 v[198:201], v134 offset:20480
	v_mfma_f32_16x16x32_f16 v[88:91], v[210:213], v[206:209], v[88:91]
	ds_read_b128 v[206:209], v134 offset:22528
	s_waitcnt lgkmcnt(5)
	v_mfma_f32_16x16x32_f16 v[138:141], v[120:123], v[112:115], v[138:141]
	ds_read_b128 v[210:213], v135 offset:55296
	s_waitcnt lgkmcnt(0)
	s_barrier
	v_mfma_f32_16x16x32_f16 v[142:145], v[194:197], v[112:115], v[142:145]
	ds_read_b128 v[32:35], v133
	v_mfma_f32_16x16x32_f16 v[108:111], v[194:197], v[190:193], v[108:111]
	ds_read_b128 v[36:39], v136 offset:32768
	v_mfma_f32_16x16x32_f16 v[154:157], v[202:205], v[112:115], v[154:157]
	ds_read_b128 v[40:43], v133 offset:2048
	v_mfma_f32_16x16x32_f16 v[64:67], v[210:213], v[112:115], v[64:67]
	v_mfma_f32_16x16x32_f16 v[112:115], v[202:205], v[190:193], v[158:161]
	ds_read_b128 v[44:47], v136 offset:34816
	v_mfma_f32_16x16x32_f16 v[158:161], v[194:197], v[198:201], v[162:165]
	ds_read_b128 v[48:51], v133 offset:4096
	v_mfma_f32_16x16x32_f16 v[76:79], v[194:197], v[206:209], v[76:79]
	ds_read_b128 v[52:55], v136 offset:36864
	v_mfma_f32_16x16x32_f16 v[162:165], v[202:205], v[198:201], v[166:169]
	ds_read_b128 v[56:59], v133 offset:6144
	v_mfma_f32_16x16x32_f16 v[84:87], v[202:205], v[206:209], v[84:87]
	ds_read_b128 v[60:63], v136 offset:38912
	s_waitcnt vmcnt(7)
	ds_write_b128 v101, v[28:31] offset:16384
	v_mfma_f32_16x16x32_f16 v[72:75], v[210:213], v[190:193], v[72:75]
	s_waitcnt vmcnt(6)
	ds_write_b128 v131, v[16:19] offset:16384
	v_mfma_f32_16x16x32_f16 v[92:95], v[120:123], v[190:193], v[92:95]
	s_waitcnt vmcnt(5)
	ds_write_b128 v132, v[20:23] offset:16384
	v_mfma_f32_16x16x32_f16 v[80:83], v[210:213], v[198:201], v[80:83]
	s_waitcnt vmcnt(4)
	ds_write_b128 v130, v[24:27] offset:16384
	v_mfma_f32_16x16x32_f16 v[88:91], v[210:213], v[206:209], v[88:91]
	s_waitcnt vmcnt(3)
	ds_write_b128 v101, v[4:7] offset:49152
	v_mfma_f32_16x16x32_f16 v[116:119], v[120:123], v[198:201], v[116:119]
	s_waitcnt vmcnt(2)
	ds_write_b128 v131, v[8:11] offset:49152
	v_mfma_f32_16x16x32_f16 v[68:71], v[120:123], v[206:209], v[68:71]
	s_waitcnt vmcnt(1)
; #define GL_LOAD(s_, kt_) if (VAR != 1) { a##s_##0 = GL_A(0, kt_); a##s_##1 = GL_A(1, kt_); a##s_##2 = GL_A(2, kt_); a##s_##3 = GL_A(3, kt_); b##s_##0 = GL_B(0, kt_); b##s_##1 = GL_B(1, kt_); b##s_##2 = GL_B(2, kt_); b##s_##3 = GL_B(3, kt_); }
; #define LDS_STORE(s_, buf_) if (VAR != 2) { LDS_ST1(sA, 0, buf_, a##s_##0) LDS_ST1(sA, 1, buf_, a##s_##1) LDS_ST1(sA, 2, buf_, a##s_##2) LDS_ST1(sA, 3, buf_, a##s_##3) LDS_ST1(sB, 0, buf_, b##s_##0) LDS_ST1(sB, 1, buf_, b##s_##1) LDS_ST1(sB, 2, buf_, b##s_##2) LDS_ST1(sB, 3, buf_, b##s_##3) }
;     ...
;   GL_LOAD(0, 0)
;   GL_LOAD(1, 1)
;   LDS_STORE(0, 0)
;   if (VAR != 4) __syncthreads();
; #pragma unroll
;   for (int kt = 0; kt < nk; kt += 2) {
;     if (kt + 2 < nk) { GL_LOAD(0, kt + 2) }
;     MMA_TILE(0)
;     LDS_STORE(1, 1)
;     if (VAR != 4) __syncthreads();
;     if (kt + 3 < nk) { GL_LOAD(1, kt + 3) }
;     MMA_TILE(1)
;     if (kt + 2 < nk) { LDS_STORE(0, 0) }
;     if (VAR != 4) __syncthreads();
	ds_write_b128 v132, v[12:15] offset:49152
	s_waitcnt lgkmcnt(13)
	v_mfma_f32_16x16x32_f16 v[120:123], v[36:39], v[32:35], v[138:141]
	s_waitcnt vmcnt(0)
	ds_write_b128 v130, v[0:3] offset:49152
	s_waitcnt lgkmcnt(12)
	v_mfma_f32_16x16x32_f16 v[138:141], v[44:47], v[32:35], v[142:145]
	s_waitcnt lgkmcnt(10)
	v_mfma_f32_16x16x32_f16 v[142:145], v[52:55], v[32:35], v[154:157]
	s_waitcnt lgkmcnt(8)
	v_mfma_f32_16x16x32_f16 v[32:35], v[60:63], v[32:35], v[64:67]
	v_mfma_f32_16x16x32_f16 v[64:67], v[36:39], v[40:43], v[92:95]
	ds_read_b128 v[154:157], v134 offset:6144
	v_mfma_f32_16x16x32_f16 v[92:95], v[44:47], v[40:43], v[108:111]
	v_mfma_f32_16x16x32_f16 v[108:111], v[52:55], v[40:43], v[112:115]
	v_mfma_f32_16x16x32_f16 v[40:43], v[60:63], v[40:43], v[72:75]
	v_mfma_f32_16x16x32_f16 v[72:75], v[36:39], v[48:51], v[116:119]
	v_mfma_f32_16x16x32_f16 v[36:39], v[36:39], v[56:59], v[68:71]
	s_nop 2
	ds_read_b128 v[68:71], v135 offset:32768
	v_mfma_f32_16x16x32_f16 v[112:115], v[44:47], v[48:51], v[158:161]
	s_nop 2
	ds_read_b128 v[158:161], v135 offset:38912
	v_mfma_f32_16x16x32_f16 v[44:47], v[44:47], v[56:59], v[76:79]
	s_nop 2
	ds_read_b128 v[76:79], v134 offset:2048
	v_mfma_f32_16x16x32_f16 v[116:119], v[52:55], v[48:51], v[162:165]
	v_mfma_f32_16x16x32_f16 v[52:55], v[52:55], v[56:59], v[84:87]
	s_nop 2
	ds_read_b128 v[84:87], v134 offset:4096
	v_mfma_f32_16x16x32_f16 v[48:51], v[60:63], v[48:51], v[80:83]
	s_nop 2
	ds_read_b128 v[80:83], v135 offset:34816
	v_mfma_f32_16x16x32_f16 v[56:59], v[60:63], v[56:59], v[88:91]
	ds_read_b128 v[60:63], v134
	s_waitcnt lgkmcnt(0)
	v_mfma_f32_16x16x32_f16 v[120:123], v[68:71], v[60:63], v[120:123]
	ds_read_b128 v[88:91], v135 offset:36864
	s_waitcnt lgkmcnt(0)
	s_barrier
	v_mfma_f32_16x16x32_f16 v[138:141], v[80:83], v[60:63], v[138:141]
	ds_read_b128 v[0:3], v133 offset:16384
	v_mfma_f32_16x16x32_f16 v[142:145], v[88:91], v[60:63], v[142:145]
	v_mfma_f32_16x16x32_f16 v[32:35], v[158:161], v[60:63], v[32:35]
	v_mfma_f32_16x16x32_f16 v[60:63], v[68:71], v[76:79], v[64:67]
	v_mfma_f32_16x16x32_f16 v[64:67], v[80:83], v[76:79], v[92:95]
	ds_read_b128 v[4:7], v136 offset:49152
	ds_read_b128 v[8:11], v133 offset:18432
	v_mfma_f32_16x16x32_f16 v[92:95], v[88:91], v[76:79], v[108:111]
	ds_read_b128 v[12:15], v136 offset:51200
	v_mfma_f32_16x16x32_f16 v[40:43], v[158:161], v[76:79], v[40:43]
	v_mfma_f32_16x16x32_f16 v[76:79], v[80:83], v[84:87], v[112:115]
	ds_read_b128 v[16:19], v133 offset:20480
	v_mfma_f32_16x16x32_f16 v[44:47], v[80:83], v[154:157], v[44:47]
	ds_read_b128 v[20:23], v136 offset:53248
	v_mfma_f32_16x16x32_f16 v[108:111], v[88:91], v[84:87], v[116:119]
	ds_read_b128 v[24:27], v133 offset:22528
	v_mfma_f32_16x16x32_f16 v[52:55], v[88:91], v[154:157], v[52:55]
	ds_read_b128 v[28:31], v136 offset:55296
	ds_read_b128 v[112:115], v135 offset:53248
	ds_read_b128 v[116:119], v134 offset:22528
	v_ashrrev_i32_e32 v101, 31, v100
	v_mfma_f32_16x16x32_f16 v[48:51], v[158:161], v[84:87], v[48:51]
	v_mfma_f32_16x16x32_f16 v[56:59], v[158:161], v[154:157], v[56:59]
	v_mfma_f32_16x16x32_f16 v[72:75], v[68:71], v[84:87], v[72:75]
	v_mfma_f32_16x16x32_f16 v[36:39], v[68:71], v[154:157], v[36:39]
	s_waitcnt lgkmcnt(8)
	v_mfma_f32_16x16x32_f16 v[68:71], v[4:7], v[0:3], v[120:123]
	s_nop 2
	ds_read_b128 v[120:123], v135 offset:55296
	s_waitcnt lgkmcnt(7)
	v_mfma_f32_16x16x32_f16 v[80:83], v[12:15], v[0:3], v[138:141]
	s_waitcnt lgkmcnt(5)
	v_mfma_f32_16x16x32_f16 v[84:87], v[20:23], v[0:3], v[142:145]
	s_waitcnt lgkmcnt(3)
	v_mfma_f32_16x16x32_f16 v[0:3], v[28:31], v[0:3], v[32:35]
	v_mfma_f32_16x16x32_f16 v[32:35], v[4:7], v[8:11], v[60:63]
	v_mfma_f32_16x16x32_f16 v[60:63], v[12:15], v[8:11], v[64:67]
	v_mfma_f32_16x16x32_f16 v[72:75], v[4:7], v[16:19], v[72:75]
	v_mfma_f32_16x16x32_f16 v[76:79], v[12:15], v[16:19], v[76:79]
	v_mfma_f32_16x16x32_f16 v[44:47], v[12:15], v[24:27], v[44:47]
	ds_read_b128 v[12:15], v134 offset:16384
	v_mfma_f32_16x16x32_f16 v[64:67], v[20:23], v[8:11], v[92:95]
	s_nop 2
	ds_read_b128 v[92:95], v135 offset:51200
	v_mfma_f32_16x16x32_f16 v[88:91], v[20:23], v[16:19], v[108:111]
	s_nop 2
	ds_read_b128 v[108:111], v134 offset:20480
	v_mfma_f32_16x16x32_f16 v[16:19], v[28:31], v[16:19], v[48:51]
	v_mfma_f32_16x16x32_f16 v[48:51], v[20:23], v[24:27], v[52:55]
	ds_read_b128 v[20:23], v134 offset:18432
	v_mfma_f32_16x16x32_f16 v[52:55], v[28:31], v[24:27], v[56:59]
	s_nop 2
	ds_read_b128 v[56:59], v135 offset:49152
	s_waitcnt lgkmcnt(0)
	s_barrier
; DI unsigned pack2(float lo, float hi) { f2_t v = {lo, hi}; h2_t b = __builtin_convertvector(v, h2_t); return __builtin_bit_cast(unsigned, b); }
; template <int VAR> DI void phase_up(const Params& P, int l, char* smem) {
;     ...
; #pragma unroll
;     for (int mt = 0; mt < 4; ++mt) {
;       const int row = row0 + mt * 16 + lr;
; #pragma unroll
;       for (int nt = 0; nt < 4; ++nt) {
;         float v[4];
; #pragma unroll
;         for (int j = 0; j < 4; ++j) { const float a = fmaxf(acc[mt][nt][j] * rs[mt], 0.f); v[j] = a * a; }
;         *(uint2*)(U + (size_t)row * DFF + col0 + nt * 16 + 4 * g) = make_uint2(pack2(v[0], v[1]), pack2(v[2], v[3]));
;       }
	s_setprio 0
	v_readlane_b32 s60, v255, 0
	v_readlane_b32 s61, v255, 1
	v_readlane_b32 s62, v255, 2
	v_readlane_b32 s63, v255, 3
	v_readlane_b32 s64, v255, 4
	v_readlane_b32 s65, v255, 5
	v_readlane_b32 s66, v255, 6
	v_readlane_b32 s67, v255, 7
	v_readlane_b32 s68, v255, 8
	v_readlane_b32 s69, v255, 9
	v_readlane_b32 s70, v255, 10
	v_readlane_b32 s71, v255, 11
	v_readlane_b32 s72, v255, 12
	v_readlane_b32 s73, v255, 13
	v_readlane_b32 s74, v255, 14
	v_readlane_b32 s75, v255, 15
	s_nop 4
	v_mfma_f32_16x16x32_f16 v[4:7], v[4:7], v[24:27], v[36:39]
	v_mfma_f32_16x16x32_f16 v[68:71], v[56:59], v[12:15], v[68:71]
	v_mfma_f32_16x16x32_f16 v[8:11], v[28:31], v[8:11], v[40:43]
	v_mfma_f32_16x16x32_f16 v[80:83], v[92:95], v[12:15], v[80:83]
	v_mfma_f32_16x16x32_f16 v[84:87], v[112:115], v[12:15], v[84:87]
	v_mfma_f32_16x16x32_f16 v[130:133], v[120:123], v[12:15], v[0:3]
	v_mfma_f32_16x16x32_f16 v[12:15], v[56:59], v[116:119], v[4:7]
	v_mfma_f32_16x16x32_f16 v[4:7], v[112:115], v[116:119], v[48:51]
	v_mfma_f32_16x16x32_f16 v[134:137], v[56:59], v[20:23], v[32:35]
	v_mfma_f32_16x16x32_f16 v[32:35], v[120:123], v[20:23], v[8:11]
	v_mfma_f32_16x16x32_f16 v[8:11], v[92:95], v[116:119], v[44:47]
	v_mfma_f32_16x16x32_f16 v[16:19], v[120:123], v[108:111], v[16:19]
	v_mfma_f32_16x16x32_f16 v[40:43], v[92:95], v[20:23], v[60:63]
	v_mfma_f32_16x16x32_f16 v[36:39], v[112:115], v[20:23], v[64:67]
	v_mfma_f32_16x16x32_f16 v[28:31], v[56:59], v[108:111], v[72:75]
	v_mfma_f32_16x16x32_f16 v[24:27], v[92:95], v[108:111], v[76:79]
	v_mfma_f32_16x16x32_f16 v[20:23], v[112:115], v[108:111], v[88:91]
	v_mfma_f32_16x16x32_f16 v[0:3], v[120:123], v[116:119], v[52:55]
	v_lshl_add_u64 v[44:45], v[100:101], 1, v[96:97]
	v_and_b32_e32 v250, 16, v148
	v_lshrrev_b32_e32 v251, 1, v250
	v_add_u32_e32 v250, v250, v251
	v_and_b32_e32 v251, 8, v148
	v_lshl_add_u32 v250, v251, 3, v250
	v_lshlrev_b32_e32 v251, 13, v251
	v_sub_u32_e32 v250, v250, v251
	v_ashrrev_i32_e32 v251, 31, v250
	v_lshl_add_u64 v[44:45], v[250:251], 0, v[44:45]
	v_mov_b32_e32 v248, 0x10000
	v_mov_b32_e32 v249, 0
	v_lshlrev_b64 v[46:47], 13, v[102:103]
	v_lshl_add_u64 v[46:47], v[44:45], 0, v[46:47]
	v_lshl_add_u64 v[48:49], v[248:249], 0, v[46:47]
	v_mul_f32_e32 v68, v128, v68
	v_mul_f32_e32 v69, v128, v69
	v_mul_f32_e32 v70, v128, v70
	v_mul_f32_e32 v71, v128, v71
	v_mul_f32_e32 v80, v128, v80
	v_mul_f32_e32 v81, v128, v81
	v_mul_f32_e32 v82, v128, v82
	v_mul_f32_e32 v83, v128, v83
	v_max_f32_e32 v68, 0, v68
	v_max_f32_e32 v69, 0, v69
	v_max_f32_e32 v70, 0, v70
	v_max_f32_e32 v71, 0, v71
	v_max_f32_e32 v80, 0, v80
	v_max_f32_e32 v81, 0, v81
	v_max_f32_e32 v82, 0, v82
	v_max_f32_e32 v83, 0, v83
	v_mul_f32_e32 v68, v68, v68
	v_mul_f32_e32 v69, v69, v69
	v_mul_f32_e32 v70, v70, v70
	v_mul_f32_e32 v71, v71, v71
	v_mul_f32_e32 v80, v80, v80
	v_mul_f32_e32 v81, v81, v81
	v_mul_f32_e32 v82, v82, v82
	v_mul_f32_e32 v83, v83, v83
	v_cvt_pk_f16_f32 v68, v68, v69
	v_cvt_pk_f16_f32 v69, v70, v71
	v_cvt_pk_f16_f32 v70, v80, v81
	v_cvt_pk_f16_f32 v71, v82, v83
	s_nop 1
	v_permlane16_swap_b32_e32 v68, v70
	v_permlane16_swap_b32_e32 v69, v71
	v_mul_f32_e32 v84, v128, v84
	v_mul_f32_e32 v85, v128, v85
	v_mul_f32_e32 v86, v128, v86
	v_mul_f32_e32 v87, v128, v87
	v_mul_f32_e32 v130, v128, v130
	v_mul_f32_e32 v131, v128, v131
	v_mul_f32_e32 v132, v128, v132
	v_mul_f32_e32 v133, v128, v133
	v_max_f32_e32 v84, 0, v84
	v_max_f32_e32 v85, 0, v85
	v_max_f32_e32 v86, 0, v86
	v_max_f32_e32 v87, 0, v87
	v_max_f32_e32 v130, 0, v130
	v_max_f32_e32 v131, 0, v131
	v_max_f32_e32 v132, 0, v132
	v_max_f32_e32 v133, 0, v133
	v_mul_f32_e32 v84, v84, v84
	v_mul_f32_e32 v85, v85, v85
	v_mul_f32_e32 v86, v86, v86
	v_mul_f32_e32 v87, v87, v87
	v_mul_f32_e32 v130, v130, v130
	v_mul_f32_e32 v131, v131, v131
	v_mul_f32_e32 v132, v132, v132
	v_mul_f32_e32 v133, v133, v133
	v_cvt_pk_f16_f32 v84, v84, v85
	v_cvt_pk_f16_f32 v85, v86, v87
	v_cvt_pk_f16_f32 v86, v130, v131
	v_cvt_pk_f16_f32 v87, v132, v133
	s_nop 1
	v_permlane16_swap_b32_e32 v84, v86
	v_permlane16_swap_b32_e32 v85, v87
	s_nop 1
	v_mov_b32_dpp v240, v68 row_ror:8 row_mask:0xf bank_mask:0x3
	v_mov_b32_dpp v241, v69 row_ror:8 row_mask:0xf bank_mask:0x3
	v_mov_b32_dpp v242, v70 row_ror:8 row_mask:0xf bank_mask:0x3
	v_mov_b32_dpp v243, v71 row_ror:8 row_mask:0xf bank_mask:0x3
	v_mov_b32_dpp v68, v84 row_ror:8 row_mask:0xf bank_mask:0xc
	v_mov_b32_dpp v69, v85 row_ror:8 row_mask:0xf bank_mask:0xc
	v_mov_b32_dpp v70, v86 row_ror:8 row_mask:0xf bank_mask:0xc
	v_mov_b32_dpp v71, v87 row_ror:8 row_mask:0xf bank_mask:0xc
	v_mov_b32_dpp v84, v240 quad_perm:[0,1,2,3] row_mask:0xf bank_mask:0x3
	v_mov_b32_dpp v85, v241 quad_perm:[0,1,2,3] row_mask:0xf bank_mask:0x3
	v_mov_b32_dpp v86, v242 quad_perm:[0,1,2,3] row_mask:0xf bank_mask:0x3
	v_mov_b32_dpp v87, v243 quad_perm:[0,1,2,3] row_mask:0xf bank_mask:0x3
	global_store_dwordx4 v[46:47], v[68:71], off
	global_store_dwordx4 v[48:49], v[84:87], off
	v_lshlrev_b64 v[46:47], 13, v[98:99]
	v_lshl_add_u64 v[46:47], v[44:45], 0, v[46:47]
	v_lshl_add_u64 v[48:49], v[248:249], 0, v[46:47]
	v_mul_f32_e32 v134, v126, v134
	v_mul_f32_e32 v135, v126, v135
	v_mul_f32_e32 v136, v126, v136
	v_mul_f32_e32 v137, v126, v137
	v_mul_f32_e32 v40, v126, v40
	v_mul_f32_e32 v41, v126, v41
	v_mul_f32_e32 v42, v126, v42
	v_mul_f32_e32 v43, v126, v43
	v_max_f32_e32 v134, 0, v134
	v_max_f32_e32 v135, 0, v135
	v_max_f32_e32 v136, 0, v136
	v_max_f32_e32 v137, 0, v137
	v_max_f32_e32 v40, 0, v40
	v_max_f32_e32 v41, 0, v41
	v_max_f32_e32 v42, 0, v42
	v_max_f32_e32 v43, 0, v43
	v_mul_f32_e32 v134, v134, v134
	v_mul_f32_e32 v135, v135, v135
	v_mul_f32_e32 v136, v136, v136
; DI unsigned pack2(float lo, float hi) { f2_t v = {lo, hi}; h2_t b = __builtin_convertvector(v, h2_t); return __builtin_bit_cast(unsigned, b); }
; template <int VAR> DI void phase_up(const Params& P, int l, char* smem) {
;     ...
; #pragma unroll
;     for (int mt = 0; mt < 4; ++mt) {
;       const int row = row0 + mt * 16 + lr;
; #pragma unroll
;       for (int nt = 0; nt < 4; ++nt) {
;         float v[4];
; #pragma unroll
;         for (int j = 0; j < 4; ++j) { const float a = fmaxf(acc[mt][nt][j] * rs[mt], 0.f); v[j] = a * a; }
;         *(uint2*)(U + (size_t)row * DFF + col0 + nt * 16 + 4 * g) = make_uint2(pack2(v[0], v[1]), pack2(v[2], v[3]));
;       }
	v_mul_f32_e32 v137, v137, v137
	v_mul_f32_e32 v40, v40, v40
	v_mul_f32_e32 v41, v41, v41
	v_mul_f32_e32 v42, v42, v42
	v_mul_f32_e32 v43, v43, v43
	v_cvt_pk_f16_f32 v244, v134, v135
	v_cvt_pk_f16_f32 v245, v136, v137
	v_cvt_pk_f16_f32 v246, v40, v41
	v_cvt_pk_f16_f32 v247, v42, v43
	s_nop 1
	v_permlane16_swap_b32_e32 v244, v246
	v_permlane16_swap_b32_e32 v245, v247
	v_mul_f32_e32 v36, v126, v36
	v_mul_f32_e32 v37, v126, v37
	v_mul_f32_e32 v38, v126, v38
	v_mul_f32_e32 v39, v126, v39
	v_mul_f32_e32 v32, v126, v32
	v_mul_f32_e32 v33, v126, v33
	v_mul_f32_e32 v34, v126, v34
	v_mul_f32_e32 v35, v126, v35
	v_max_f32_e32 v36, 0, v36
	v_max_f32_e32 v37, 0, v37
	v_max_f32_e32 v38, 0, v38
	v_max_f32_e32 v39, 0, v39
	v_max_f32_e32 v32, 0, v32
	v_max_f32_e32 v33, 0, v33
	v_max_f32_e32 v34, 0, v34
	v_max_f32_e32 v35, 0, v35
	v_mul_f32_e32 v36, v36, v36
	v_mul_f32_e32 v37, v37, v37
	v_mul_f32_e32 v38, v38, v38
	v_mul_f32_e32 v39, v39, v39
	v_mul_f32_e32 v32, v32, v32
	v_mul_f32_e32 v33, v33, v33
	v_mul_f32_e32 v34, v34, v34
	v_mul_f32_e32 v35, v35, v35
	v_cvt_pk_f16_f32 v36, v36, v37
	v_cvt_pk_f16_f32 v37, v38, v39
	v_cvt_pk_f16_f32 v38, v32, v33
	v_cvt_pk_f16_f32 v39, v34, v35
	s_nop 1
	v_permlane16_swap_b32_e32 v36, v38
	v_permlane16_swap_b32_e32 v37, v39
	s_nop 1
	v_mov_b32_dpp v240, v244 row_ror:8 row_mask:0xf bank_mask:0x3
	v_mov_b32_dpp v241, v245 row_ror:8 row_mask:0xf bank_mask:0x3
	v_mov_b32_dpp v242, v246 row_ror:8 row_mask:0xf bank_mask:0x3
	v_mov_b32_dpp v243, v247 row_ror:8 row_mask:0xf bank_mask:0x3
	v_mov_b32_dpp v244, v36 row_ror:8 row_mask:0xf bank_mask:0xc
	v_mov_b32_dpp v245, v37 row_ror:8 row_mask:0xf bank_mask:0xc
	v_mov_b32_dpp v246, v38 row_ror:8 row_mask:0xf bank_mask:0xc
	v_mov_b32_dpp v247, v39 row_ror:8 row_mask:0xf bank_mask:0xc
	v_mov_b32_dpp v36, v240 quad_perm:[0,1,2,3] row_mask:0xf bank_mask:0x3
	v_mov_b32_dpp v37, v241 quad_perm:[0,1,2,3] row_mask:0xf bank_mask:0x3
	v_mov_b32_dpp v38, v242 quad_perm:[0,1,2,3] row_mask:0xf bank_mask:0x3
	v_mov_b32_dpp v39, v243 quad_perm:[0,1,2,3] row_mask:0xf bank_mask:0x3
	global_store_dwordx4 v[46:47], v[244:247], off
	global_store_dwordx4 v[48:49], v[36:39], off
	v_lshlrev_b64 v[46:47], 13, v[106:107]
	v_lshl_add_u64 v[46:47], v[44:45], 0, v[46:47]
	v_lshl_add_u64 v[48:49], v[248:249], 0, v[46:47]
	v_mul_f32_e32 v28, v129, v28
	v_mul_f32_e32 v29, v129, v29
	v_mul_f32_e32 v30, v129, v30
	v_mul_f32_e32 v31, v129, v31
	v_mul_f32_e32 v24, v129, v24
	v_mul_f32_e32 v25, v129, v25
	v_mul_f32_e32 v26, v129, v26
	v_mul_f32_e32 v27, v129, v27
	v_max_f32_e32 v28, 0, v28
	v_max_f32_e32 v29, 0, v29
	v_max_f32_e32 v30, 0, v30
	v_max_f32_e32 v31, 0, v31
	v_max_f32_e32 v24, 0, v24
	v_max_f32_e32 v25, 0, v25
	v_max_f32_e32 v26, 0, v26
	v_max_f32_e32 v27, 0, v27
	v_mul_f32_e32 v28, v28, v28
	v_mul_f32_e32 v29, v29, v29
	v_mul_f32_e32 v30, v30, v30
	v_mul_f32_e32 v31, v31, v31
	v_mul_f32_e32 v24, v24, v24
	v_mul_f32_e32 v25, v25, v25
	v_mul_f32_e32 v26, v26, v26
	v_mul_f32_e32 v27, v27, v27
	v_cvt_pk_f16_f32 v28, v28, v29
	v_cvt_pk_f16_f32 v29, v30, v31
	v_cvt_pk_f16_f32 v30, v24, v25
	v_cvt_pk_f16_f32 v31, v26, v27
	s_nop 1
	v_permlane16_swap_b32_e32 v28, v30
	v_permlane16_swap_b32_e32 v29, v31
	v_mul_f32_e32 v20, v129, v20
	v_mul_f32_e32 v21, v129, v21
	v_mul_f32_e32 v22, v129, v22
	v_mul_f32_e32 v23, v129, v23
	v_mul_f32_e32 v16, v129, v16
	v_mul_f32_e32 v17, v129, v17
	v_mul_f32_e32 v18, v129, v18
	v_mul_f32_e32 v19, v129, v19
	v_max_f32_e32 v20, 0, v20
	v_max_f32_e32 v21, 0, v21
	v_max_f32_e32 v22, 0, v22
	v_max_f32_e32 v23, 0, v23
	v_max_f32_e32 v16, 0, v16
	v_max_f32_e32 v17, 0, v17
	v_max_f32_e32 v18, 0, v18
	v_max_f32_e32 v19, 0, v19
	v_mul_f32_e32 v20, v20, v20
	v_mul_f32_e32 v21, v21, v21
	v_mul_f32_e32 v22, v22, v22
	v_mul_f32_e32 v23, v23, v23
	v_mul_f32_e32 v16, v16, v16
	v_mul_f32_e32 v17, v17, v17
	v_mul_f32_e32 v18, v18, v18
; DI unsigned pack2(float lo, float hi) { f2_t v = {lo, hi}; h2_t b = __builtin_convertvector(v, h2_t); return __builtin_bit_cast(unsigned, b); }
; template <int VAR> DI void phase_up(const Params& P, int l, char* smem) {
;     ...
; #pragma unroll
;     for (int mt = 0; mt < 4; ++mt) {
;       const int row = row0 + mt * 16 + lr;
; #pragma unroll
;       for (int nt = 0; nt < 4; ++nt) {
;         float v[4];
; #pragma unroll
;         for (int j = 0; j < 4; ++j) { const float a = fmaxf(acc[mt][nt][j] * rs[mt], 0.f); v[j] = a * a; }
;         *(uint2*)(U + (size_t)row * DFF + col0 + nt * 16 + 4 * g) = make_uint2(pack2(v[0], v[1]), pack2(v[2], v[3]));
;       }
	v_mul_f32_e32 v19, v19, v19
	v_cvt_pk_f16_f32 v20, v20, v21
	v_cvt_pk_f16_f32 v21, v22, v23
	v_cvt_pk_f16_f32 v22, v16, v17
	v_cvt_pk_f16_f32 v23, v18, v19
	s_nop 1
	v_permlane16_swap_b32_e32 v20, v22
	v_permlane16_swap_b32_e32 v21, v23
	s_nop 1
	v_mov_b32_dpp v240, v28 row_ror:8 row_mask:0xf bank_mask:0x3
	v_mov_b32_dpp v241, v29 row_ror:8 row_mask:0xf bank_mask:0x3
	v_mov_b32_dpp v242, v30 row_ror:8 row_mask:0xf bank_mask:0x3
	v_mov_b32_dpp v243, v31 row_ror:8 row_mask:0xf bank_mask:0x3
	v_mov_b32_dpp v28, v20 row_ror:8 row_mask:0xf bank_mask:0xc
	v_mov_b32_dpp v29, v21 row_ror:8 row_mask:0xf bank_mask:0xc
	v_mov_b32_dpp v30, v22 row_ror:8 row_mask:0xf bank_mask:0xc
	v_mov_b32_dpp v31, v23 row_ror:8 row_mask:0xf bank_mask:0xc
	v_mov_b32_dpp v20, v240 quad_perm:[0,1,2,3] row_mask:0xf bank_mask:0x3
	v_mov_b32_dpp v21, v241 quad_perm:[0,1,2,3] row_mask:0xf bank_mask:0x3
	v_mov_b32_dpp v22, v242 quad_perm:[0,1,2,3] row_mask:0xf bank_mask:0x3
	v_mov_b32_dpp v23, v243 quad_perm:[0,1,2,3] row_mask:0xf bank_mask:0x3
	global_store_dwordx4 v[46:47], v[28:31], off
	global_store_dwordx4 v[48:49], v[20:23], off
	v_lshlrev_b64 v[46:47], 13, v[104:105]
	v_lshl_add_u64 v[46:47], v[44:45], 0, v[46:47]
	v_lshl_add_u64 v[48:49], v[248:249], 0, v[46:47]
	v_mul_f32_e32 v12, v127, v12
	v_mul_f32_e32 v13, v127, v13
	v_mul_f32_e32 v14, v127, v14
	v_mul_f32_e32 v15, v127, v15
	v_mul_f32_e32 v8, v127, v8
	v_mul_f32_e32 v9, v127, v9
	v_mul_f32_e32 v10, v127, v10
	v_mul_f32_e32 v11, v127, v11
	v_max_f32_e32 v12, 0, v12
	v_max_f32_e32 v13, 0, v13
	v_max_f32_e32 v14, 0, v14
	v_max_f32_e32 v15, 0, v15
	v_max_f32_e32 v8, 0, v8
	v_max_f32_e32 v9, 0, v9
	v_max_f32_e32 v10, 0, v10
	v_max_f32_e32 v11, 0, v11
	v_mul_f32_e32 v12, v12, v12
	v_mul_f32_e32 v13, v13, v13
	v_mul_f32_e32 v14, v14, v14
	v_mul_f32_e32 v15, v15, v15
	v_mul_f32_e32 v8, v8, v8
	v_mul_f32_e32 v9, v9, v9
	v_mul_f32_e32 v10, v10, v10
	v_mul_f32_e32 v11, v11, v11
	v_cvt_pk_f16_f32 v12, v12, v13
	v_cvt_pk_f16_f32 v13, v14, v15
	v_cvt_pk_f16_f32 v14, v8, v9
	v_cvt_pk_f16_f32 v15, v10, v11
	s_nop 1
	v_permlane16_swap_b32_e32 v12, v14
	v_permlane16_swap_b32_e32 v13, v15
	v_mul_f32_e32 v4, v127, v4
	v_mul_f32_e32 v5, v127, v5
	v_mul_f32_e32 v6, v127, v6
	v_mul_f32_e32 v7, v127, v7
	v_mul_f32_e32 v0, v127, v0
	v_mul_f32_e32 v1, v127, v1
	v_mul_f32_e32 v2, v127, v2
	v_mul_f32_e32 v3, v127, v3
	v_max_f32_e32 v4, 0, v4
	v_max_f32_e32 v5, 0, v5
	v_max_f32_e32 v6, 0, v6
	v_max_f32_e32 v7, 0, v7
	v_max_f32_e32 v0, 0, v0
	v_max_f32_e32 v1, 0, v1
	v_max_f32_e32 v2, 0, v2
	v_max_f32_e32 v3, 0, v3
	v_mul_f32_e32 v4, v4, v4
	v_mul_f32_e32 v5, v5, v5
	v_mul_f32_e32 v6, v6, v6
	v_mul_f32_e32 v7, v7, v7
	v_mul_f32_e32 v0, v0, v0
	v_mul_f32_e32 v1, v1, v1
	v_mul_f32_e32 v2, v2, v2
	v_mul_f32_e32 v3, v3, v3
	v_cvt_pk_f16_f32 v4, v4, v5
	v_cvt_pk_f16_f32 v5, v6, v7
	v_cvt_pk_f16_f32 v6, v0, v1
	v_cvt_pk_f16_f32 v7, v2, v3
	s_nop 1
	v_permlane16_swap_b32_e32 v4, v6
	v_permlane16_swap_b32_e32 v5, v7
	s_nop 1
	v_mov_b32_dpp v240, v12 row_ror:8 row_mask:0xf bank_mask:0x3
	v_mov_b32_dpp v241, v13 row_ror:8 row_mask:0xf bank_mask:0x3
	v_mov_b32_dpp v242, v14 row_ror:8 row_mask:0xf bank_mask:0x3
	v_mov_b32_dpp v243, v15 row_ror:8 row_mask:0xf bank_mask:0x3
	v_mov_b32_dpp v12, v4 row_ror:8 row_mask:0xf bank_mask:0xc
	v_mov_b32_dpp v13, v5 row_ror:8 row_mask:0xf bank_mask:0xc
	v_mov_b32_dpp v14, v6 row_ror:8 row_mask:0xf bank_mask:0xc
	v_mov_b32_dpp v15, v7 row_ror:8 row_mask:0xf bank_mask:0xc
	v_mov_b32_dpp v4, v240 quad_perm:[0,1,2,3] row_mask:0xf bank_mask:0x3
	v_mov_b32_dpp v5, v241 quad_perm:[0,1,2,3] row_mask:0xf bank_mask:0x3
	v_mov_b32_dpp v6, v242 quad_perm:[0,1,2,3] row_mask:0xf bank_mask:0x3
	v_mov_b32_dpp v7, v243 quad_perm:[0,1,2,3] row_mask:0xf bank_mask:0x3
	global_store_dwordx4 v[46:47], v[12:15], off
	global_store_dwordx4 v[48:49], v[4:7], off
	s_branch .LBB0_1312
